# FFN-up epilogue: post-store vmcnt(0) relaxed to vmcnt(2) where only two stores are outstanding; remaining dead DPP inits removed
# baseline (speedup 1.0000x reference)
;     __device__ __forceinline__ void operator()(AccRef acc, const Unit& u, int wr, int wc, int fr, int fq) const {
;     ...
;             for (int n = 0; n < 2; ++n) { const unsigned jn = (unsigned)(j0 + 4 * n);
;                 f32x4 cu[4];
;                 {
;                     const f32x4 wu0 = *(const f32x4*)(cw + (DFF + jn)), wu1 = *(const f32x4*)(cw + (UPN + DFF + jn)), wu2 = *(const f32x4*)(cw + (2 * UPN + DFF + jn)), bu = *(const f32x4*)(cb + (DFF + jn));
;                     f32x4 pu1 = (f32x4){0.f, 0.f, 0.f, 0.f}, pu2 = pu1;
; #pragma unroll
;                     for (int m = 0; m < 4; ++m) {
;                         const f32x4 au = unpack4(pa[ai][1][m][n]);
;                         const f32x4 ru1 = ror1v(au), ru2 = ror2v(au);
;                         const f32x4 u1 = fr >= 1 ? ru1 : pu1, u2 = fr >= 2 ? ru2 : pu2;
;                         if (m == 0 && fr < 2) *(f32x4*)(edge + (unsigned)((grp * 4 + fr) * UPN + DFF + jn)) = au;
;                         if (m == 3 && fr >= 14) *(f32x4*)(edge + (unsigned)((grp * 4 + (fr - 12)) * UPN + DFF + jn)) = au;
;                         cu[m] = bu + wu0 * u2 + wu1 * u1 + wu2 * au;
;                         pu1 = ru1; pu2 = ru2; }
;                 }
;                 {
;                     const f32x4 wg0 = *(const f32x4*)(cw + jn), wg1 = *(const f32x4*)(cw + (UPN + jn)), wg2 = *(const f32x4*)(cw + (2 * UPN + jn)), bg = *(const f32x4*)(cb + jn);
;                     f32x4 pg1 = (f32x4){0.f, 0.f, 0.f, 0.f}, pg2 = pg1;
; #pragma unroll
;                     for (int m = 0; m < 4; ++m) { const int row = rowg + m * 16 + fr;
;                         const f32x4 ag = unpack4(pa[ai][0][m][n]);
;                         const f32x4 rg1 = ror1v(ag), rg2 = ror2v(ag);
;                         const f32x4 g1 = fr >= 1 ? rg1 : pg1, g2 = fr >= 2 ? rg2 : pg2;
;                         if (m == 0 && fr < 2) *(f32x4*)(edge + (unsigned)((grp * 4 + fr) * UPN + jn)) = ag;
;                         if (m == 3 && fr >= 14) *(f32x4*)(edge + (unsigned)((grp * 4 + (fr - 12)) * UPN + jn)) = ag;
;                         const f32x4 o = gelu4(bg + wg0 * g2 + wg1 * g1 + wg2 * ag) * cu[m];
;                         if (!(m == 0 && fr < 2)) *(u32x2*)(act + (unsigned)(row * DFF + jn)) = pack4(o);
;                         pg1 = rg1; pg2 = rg2; }
.LBB0_557:
	s_or_b64 exec, exec, s[0:1]
	s_nop 0
	v_cndmask_b32_e64 v43, v197, v203, s[6:7]
	v_cndmask_b32_e64 v42, v193, v199, s[6:7]
	v_cndmask_b32_e64 v37, v194, v200, s[8:9]
	v_cndmask_b32_e64 v36, v191, v195, s[8:9]
	v_cndmask_b32_e64 v41, v204, v206, s[6:7]
	v_cndmask_b32_e64 v40, v201, v205, s[6:7]
	s_waitcnt vmcnt(4)
	v_pk_fma_f32 v[42:43], v[8:9], v[42:43], v[12:13]
	v_cndmask_b32_e64 v39, v196, v202, s[8:9]
	v_cndmask_b32_e64 v38, v192, v198, s[8:9]
	v_pk_fma_f32 v[40:41], v[10:11], v[40:41], v[14:15]
	v_pk_fma_f32 v[36:37], v[0:1], v[36:37], v[42:43]
	v_pk_fma_f32 v[38:39], v[2:3], v[38:39], v[40:41]
	v_pk_fma_f32 v[36:37], v[4:5], v[68:69], v[36:37]
	v_cndmask_b32_e64 v69, v203, v178, s[6:7]
	v_cndmask_b32_e64 v68, v199, v83, s[6:7]
	v_pk_fma_f32 v[38:39], v[6:7], v[66:67], v[38:39]
	v_cndmask_b32_e64 v41, v200, v87, s[8:9]
	v_cndmask_b32_e64 v40, v195, v79, s[8:9]
	v_cndmask_b32_e64 v67, v206, v180, s[6:7]
	v_cndmask_b32_e64 v66, v205, v179, s[6:7]
	v_pk_fma_f32 v[68:69], v[8:9], v[68:69], v[12:13]
	v_cndmask_b32_e64 v43, v202, v177, s[8:9]
	v_cndmask_b32_e64 v42, v198, v82, s[8:9]
	v_pk_fma_f32 v[66:67], v[10:11], v[66:67], v[14:15]
	v_pk_fma_f32 v[40:41], v[0:1], v[40:41], v[68:69]
	v_pk_fma_f32 v[42:43], v[2:3], v[42:43], v[66:67]
	v_pk_fma_f32 v[68:69], v[4:5], v[62:63], v[40:41]
	v_lshlrev_b32_e32 v40, 16, v175
	v_and_b32_e32 v41, 0xffff0000, v175
	s_nop 1
	v_pk_fma_f32 v[190:191], v[6:7], v[50:51], v[42:43]
	v_lshlrev_b32_e32 v42, 16, v174
	v_and_b32_e32 v43, 0xffff0000, v174
	s_nop 1
	v_mov_b32_dpp v193, v40 row_ror:2 row_mask:0xf bank_mask:0xf
	v_mov_b32_dpp v194, v41 row_ror:2 row_mask:0xf bank_mask:0xf
	v_mov_b32_dpp v174, v40 row_ror:1 row_mask:0xf bank_mask:0xf
	v_mov_b32_dpp v175, v41 row_ror:1 row_mask:0xf bank_mask:0xf
	v_cndmask_b32_e64 v67, v75, v194, s[6:7]
	v_cndmask_b32_e64 v66, v74, v193, s[6:7]
	v_cndmask_b32_e64 v63, v71, v175, s[8:9]
	v_cndmask_b32_e64 v62, v70, v174, s[8:9]
	s_waitcnt vmcnt(2)
	v_pk_fma_f32 v[66:67], v[28:29], v[66:67], v[32:33]
	s_nop 1
	v_pk_fma_f32 v[62:63], v[20:21], v[62:63], v[66:67]
	s_nop 1
	v_pk_fma_f32 v[40:41], v[24:25], v[40:41], v[62:63]
	s_nop 1
	v_and_b32_e32 v67, 0x7fffffff, v41
	v_and_b32_e32 v66, 0x7fffffff, v40
	v_pk_fma_f32 v[66:67], v[66:67], s[42:43], 1.0 op_sel_hi:[1,0,0]
	s_nop 1
	v_mov_b32_dpp v195, v42 row_ror:2 row_mask:0xf bank_mask:0xf
	v_mov_b32_dpp v196, v43 row_ror:2 row_mask:0xf bank_mask:0xf
	v_rcp_f32_e32 v66, v66
	v_rcp_f32_e32 v67, v67
	v_mov_b32_dpp v189, v42 row_ror:1 row_mask:0xf bank_mask:0xf
	v_mov_b32_dpp v192, v43 row_ror:1 row_mask:0xf bank_mask:0xf
	v_cndmask_b32_e64 v71, v77, v196, s[6:7]
	v_cndmask_b32_e64 v70, v76, v195, s[6:7]
	v_cndmask_b32_e64 v51, v73, v192, s[8:9]
	v_cndmask_b32_e64 v50, v72, v189, s[8:9]
	v_pk_fma_f32 v[70:71], v[30:31], v[70:71], v[34:35]
	v_pk_mul_f32 v[62:63], v[40:41], v[40:41]
	v_pk_fma_f32 v[50:51], v[22:23], v[50:51], v[70:71]
	v_mov_b64_e32 v[70:71], s[54:55]
	v_pk_mul_f32 v[62:63], v[62:63], s[38:39] op_sel_hi:[1,0]
	v_pk_fma_f32 v[72:73], v[66:67], s[52:53], v[70:71] op_sel_hi:[1,0,0]
	v_exp_f32_e32 v62, v62
	v_exp_f32_e32 v63, v63
	v_pk_fma_f32 v[72:73], v[66:67], v[72:73], s[56:57] op_sel_hi:[1,1,0]
	v_cmp_gt_f32_e64 s[0:1], 0, v40
	v_pk_fma_f32 v[72:73], v[66:67], v[72:73], s[62:63] op_sel_hi:[1,1,0]
	v_pk_fma_f32 v[42:43], v[26:27], v[42:43], v[50:51]
	v_pk_fma_f32 v[72:73], v[66:67], v[72:73], s[64:65] op_sel_hi:[1,1,0]
	v_pk_mul_f32 v[50:51], v[42:43], v[42:43]
	v_pk_mul_f32 v[66:67], v[66:67], v[72:73]
	v_pk_mul_f32 v[50:51], v[50:51], s[38:39] op_sel_hi:[1,0]
	v_pk_mul_f32 v[62:63], v[62:63], v[66:67]
	v_exp_f32_e32 v50, v50
	v_pk_mul_f32 v[66:67], v[40:41], v[62:63]
	v_pk_fma_f32 v[62:63], v[40:41], v[62:63], v[40:41] neg_lo:[1,0,0] neg_hi:[1,0,0]
	v_exp_f32_e32 v51, v51
	v_cndmask_b32_e64 v40, v62, v66, s[0:1]
	v_cmp_gt_f32_e64 s[0:1], 0, v41
	v_and_b32_e32 v62, 0x7fffffff, v42
	v_mul_lo_u32 v45, v148, s88
	v_cndmask_b32_e64 v41, v63, v67, s[0:1]
	v_and_b32_e32 v63, 0x7fffffff, v43
	v_pk_fma_f32 v[62:63], v[62:63], s[42:43], 1.0 op_sel_hi:[1,0,0]
	v_cmp_gt_f32_e64 s[0:1], 0, v42
	v_rcp_f32_e32 v62, v62
	v_rcp_f32_e32 v63, v63
	v_pk_mul_f32 v[36:37], v[36:37], v[40:41]
	v_add_u32_e32 v136, v45, v44
	v_cvt_pk_bf16_f32 v36, v36, v37
	v_pk_fma_f32 v[66:67], v[62:63], s[52:53], v[70:71] op_sel_hi:[1,0,0]
	s_nop 1
	v_pk_fma_f32 v[66:67], v[62:63], v[66:67], s[56:57] op_sel_hi:[1,1,0]
	s_nop 1
	v_pk_fma_f32 v[66:67], v[62:63], v[66:67], s[62:63] op_sel_hi:[1,1,0]
	s_nop 0
	v_pk_fma_f32 v[66:67], v[62:63], v[66:67], s[64:65] op_sel_hi:[1,1,0]
	s_nop 0
	v_pk_mul_f32 v[62:63], v[62:63], v[66:67]
	s_nop 1
	v_pk_mul_f32 v[50:51], v[50:51], v[62:63]
	s_nop 1
	v_pk_mul_f32 v[62:63], v[42:43], v[50:51]
	v_pk_fma_f32 v[50:51], v[42:43], v[50:51], v[42:43] neg_lo:[1,0,0] neg_hi:[1,0,0]
; __device__ __forceinline__ f32x4 gelu4(f32x4 v) { const f32x2 a = gelu_pk((f32x2){v[0], v[1]}), b = gelu_pk((f32x2){v[2], v[3]}); return (f32x4){a.x, a.y, b.x, b.y}; }
; __device__ __forceinline__ f32x4 ror1v(f32x4 v) { return (f32x4){dpp_ror1(v[0]), dpp_ror1(v[1]), dpp_ror1(v[2]), dpp_ror1(v[3])}; }
; __device__ __forceinline__ f32x4 ror2v(f32x4 v) { return (f32x4){dpp_ror2(v[0]), dpp_ror2(v[1]), dpp_ror2(v[2]), dpp_ror2(v[3])}; }
; __device__ __forceinline__ u32x2 pack4(f32x4 v) { return (u32x2){pk2(v[0], v[1]), pk2(v[2], v[3])}; }
;     __device__ __forceinline__ void operator()(AccRef acc, const Unit& u, int wr, int wc, int fr, int fq) const {
;     ...
;                         const f32x4 au = unpack4(pa[ai][1][m][n]);
;                         const f32x4 ru1 = ror1v(au), ru2 = ror2v(au);
;                         const f32x4 u1 = fr >= 1 ? ru1 : pu1, u2 = fr >= 2 ? ru2 : pu2;
;                         if (m == 0 && fr < 2) *(f32x4*)(edge + (unsigned)((grp * 4 + fr) * UPN + DFF + jn)) = au;
;                         if (m == 3 && fr >= 14) *(f32x4*)(edge + (unsigned)((grp * 4 + (fr - 12)) * UPN + DFF + jn)) = au;
;                         cu[m] = bu + wu0 * u2 + wu1 * u1 + wu2 * au;
;                         pu1 = ru1; pu2 = ru2; }
;                 }
;                 {
;                     const f32x4 wg0 = *(const f32x4*)(cw + jn), wg1 = *(const f32x4*)(cw + (UPN + jn)), wg2 = *(const f32x4*)(cw + (2 * UPN + jn)), bg = *(const f32x4*)(cb + jn);
;                     f32x4 pg1 = (f32x4){0.f, 0.f, 0.f, 0.f}, pg2 = pg1;
; #pragma unroll
;                     for (int m = 0; m < 4; ++m) { const int row = rowg + m * 16 + fr;
;                         const f32x4 ag = unpack4(pa[ai][0][m][n]);
;                         const f32x4 rg1 = ror1v(ag), rg2 = ror2v(ag);
;                         const f32x4 g1 = fr >= 1 ? rg1 : pg1, g2 = fr >= 2 ? rg2 : pg2;
;                         if (m == 0 && fr < 2) *(f32x4*)(edge + (unsigned)((grp * 4 + fr) * UPN + jn)) = ag;
;                         if (m == 3 && fr >= 14) *(f32x4*)(edge + (unsigned)((grp * 4 + (fr - 12)) * UPN + jn)) = ag;
;                         const f32x4 o = gelu4(bg + wg0 * g2 + wg1 * g1 + wg2 * ag) * cu[m];
;                         if (!(m == 0 && fr < 2)) *(u32x2*)(act + (unsigned)(row * DFF + jn)) = pack4(o);
;                         pg1 = rg1; pg2 = rg2; }
	s_nop 0
	v_cndmask_b32_e64 v42, v50, v62, s[0:1]
	v_cmp_gt_f32_e64 s[0:1], 0, v43
	s_nop 1
	v_cndmask_b32_e64 v43, v51, v63, s[0:1]
	v_pk_mul_f32 v[38:39], v[38:39], v[42:43]
	s_nop 1
	v_cvt_pk_bf16_f32 v37, v38, v39
	v_lshl_add_u64 v[38:39], v[136:137], 1, s[26:27]
	global_store_dwordx2 v[38:39], v[36:37], off
	v_lshlrev_b32_e32 v36, 16, v173
	v_and_b32_e32 v37, 0xffff0000, v173
	s_nop 1
	v_mov_b32_dpp v43, v36 row_ror:2 row_mask:0xf bank_mask:0xf
	v_mov_b32_dpp v40, v36 row_ror:1 row_mask:0xf bank_mask:0xf
	v_mov_b32_dpp v63, v37 row_ror:2 row_mask:0xf bank_mask:0xf
	v_mov_b32_dpp v41, v37 row_ror:1 row_mask:0xf bank_mask:0xf
	v_cndmask_b32_e64 v77, v194, v63, s[6:7]
	v_cndmask_b32_e64 v76, v193, v43, s[6:7]
	v_cndmask_b32_e64 v75, v175, v41, s[8:9]
	v_cndmask_b32_e64 v74, v174, v40, s[8:9]
	v_pk_fma_f32 v[76:77], v[28:29], v[76:77], v[32:33]
	v_lshlrev_b32_e32 v38, 16, v172
	v_pk_fma_f32 v[74:75], v[20:21], v[74:75], v[76:77]
	v_and_b32_e32 v39, 0xffff0000, v172
	v_pk_fma_f32 v[36:37], v[24:25], v[36:37], v[74:75]
	s_nop 1
	v_and_b32_e32 v77, 0x7fffffff, v37
	v_and_b32_e32 v76, 0x7fffffff, v36
	v_pk_fma_f32 v[76:77], v[76:77], s[42:43], 1.0 op_sel_hi:[1,0,0]
	v_mov_b32_dpp v50, v38 row_ror:2 row_mask:0xf bank_mask:0xf
	v_rcp_f32_e32 v76, v76
	v_rcp_f32_e32 v77, v77
	v_mov_b32_dpp v66, v39 row_ror:2 row_mask:0xf bank_mask:0xf
	v_mov_b32_dpp v42, v38 row_ror:1 row_mask:0xf bank_mask:0xf
	v_mov_b32_dpp v62, v39 row_ror:1 row_mask:0xf bank_mask:0xf
	v_cndmask_b32_e64 v173, v196, v66, s[6:7]
	v_cndmask_b32_e64 v172, v195, v50, s[6:7]
	v_cndmask_b32_e64 v73, v192, v62, s[8:9]
	v_cndmask_b32_e64 v72, v189, v42, s[8:9]
	v_pk_fma_f32 v[172:173], v[30:31], v[172:173], v[34:35]
	v_pk_mul_f32 v[74:75], v[36:37], v[36:37]
	v_pk_fma_f32 v[72:73], v[22:23], v[72:73], v[172:173]
	v_pk_mul_f32 v[74:75], v[74:75], s[38:39] op_sel_hi:[1,0]
	v_pk_fma_f32 v[172:173], v[76:77], s[52:53], v[70:71] op_sel_hi:[1,0,0]
	v_exp_f32_e32 v74, v74
	v_exp_f32_e32 v75, v75
	v_pk_fma_f32 v[172:173], v[76:77], v[172:173], s[56:57] op_sel_hi:[1,1,0]
	v_cmp_gt_f32_e64 s[0:1], 0, v36
	v_pk_fma_f32 v[172:173], v[76:77], v[172:173], s[62:63] op_sel_hi:[1,1,0]
	v_pk_fma_f32 v[38:39], v[26:27], v[38:39], v[72:73]
	v_pk_fma_f32 v[172:173], v[76:77], v[172:173], s[64:65] op_sel_hi:[1,1,0]
	v_pk_mul_f32 v[72:73], v[38:39], v[38:39]
	v_pk_mul_f32 v[76:77], v[76:77], v[172:173]
	v_pk_mul_f32 v[72:73], v[72:73], s[38:39] op_sel_hi:[1,0]
	v_pk_mul_f32 v[74:75], v[74:75], v[76:77]
	v_exp_f32_e32 v72, v72
	v_pk_mul_f32 v[76:77], v[36:37], v[74:75]
	v_pk_fma_f32 v[74:75], v[36:37], v[74:75], v[36:37] neg_lo:[1,0,0] neg_hi:[1,0,0]
	v_exp_f32_e32 v73, v73
	v_cndmask_b32_e64 v36, v74, v76, s[0:1]
	v_cmp_gt_f32_e64 s[0:1], 0, v37
	v_and_b32_e32 v74, 0x7fffffff, v38
	v_add_u32_e32 v51, 0xb000, v45
	v_cndmask_b32_e64 v37, v75, v77, s[0:1]
	v_and_b32_e32 v75, 0x7fffffff, v39
	v_pk_fma_f32 v[74:75], v[74:75], s[42:43], 1.0 op_sel_hi:[1,0,0]
	v_cmp_gt_f32_e64 s[0:1], 0, v38
	v_rcp_f32_e32 v74, v74
	v_rcp_f32_e32 v75, v75
	v_pk_mul_f32 v[36:37], v[68:69], v[36:37]
	v_add_u32_e32 v136, v51, v44
	v_cvt_pk_bf16_f32 v36, v36, v37
	v_pk_fma_f32 v[70:71], v[74:75], s[52:53], v[70:71] op_sel_hi:[1,0,0]
	s_nop 1
	v_pk_fma_f32 v[70:71], v[74:75], v[70:71], s[56:57] op_sel_hi:[1,1,0]
	s_nop 1
	v_pk_fma_f32 v[70:71], v[74:75], v[70:71], s[62:63] op_sel_hi:[1,1,0]
	s_nop 0
	v_pk_fma_f32 v[70:71], v[74:75], v[70:71], s[64:65] op_sel_hi:[1,1,0]
	s_nop 0
	v_pk_mul_f32 v[70:71], v[74:75], v[70:71]
	s_nop 1
	v_pk_mul_f32 v[70:71], v[72:73], v[70:71]
	s_nop 0
	v_pk_mul_f32 v[72:73], v[38:39], v[70:71]
	v_pk_fma_f32 v[70:71], v[38:39], v[70:71], v[38:39] neg_lo:[1,0,0] neg_hi:[1,0,0]
	s_nop 0
	v_cndmask_b32_e64 v38, v70, v72, s[0:1]
	v_cmp_gt_f32_e64 s[0:1], 0, v39
	s_nop 1
	v_cndmask_b32_e64 v39, v71, v73, s[0:1]
	v_pk_mul_f32 v[38:39], v[190:191], v[38:39]
	s_nop 1
	v_cvt_pk_bf16_f32 v37, v38, v39
	v_lshl_add_u64 v[38:39], v[136:137], 1, s[26:27]
	global_store_dwordx2 v[38:39], v[36:37], off
	v_lshlrev_b32_e32 v36, 16, v80
	v_and_b32_e32 v37, 0xffff0000, v80
	v_lshlrev_b32_e32 v38, 16, v81
	v_and_b32_e32 v39, 0xffff0000, v81
	s_nop 1
	v_mov_b32_dpp v67, v36 row_ror:1 row_mask:0xf bank_mask:0xf
	v_mov_b32_dpp v68, v37 row_ror:1 row_mask:0xf bank_mask:0xf
	v_mov_b32_dpp v69, v38 row_ror:1 row_mask:0xf bank_mask:0xf
	v_mov_b32_dpp v72, v39 row_ror:1 row_mask:0xf bank_mask:0xf
	v_mov_b32_dpp v70, v36 row_ror:2 row_mask:0xf bank_mask:0xf
	v_mov_b32_dpp v73, v37 row_ror:2 row_mask:0xf bank_mask:0xf
	v_mov_b32_dpp v71, v38 row_ror:2 row_mask:0xf bank_mask:0xf
	v_mov_b32_dpp v74, v39 row_ror:2 row_mask:0xf bank_mask:0xf
	s_and_saveexec_b64 s[0:1], vcc
	s_cbranch_execz .LBB0_559
	v_add_u32_e32 v136, v150, v44
	v_lshl_add_u64 v[76:77], v[136:137], 2, s[28:29]
	global_store_dwordx4 v[76:77], v[36:39], off

; __device__ __forceinline__ f32x4 gelu4(f32x4 v) { const f32x2 a = gelu_pk((f32x2){v[0], v[1]}), b = gelu_pk((f32x2){v[2], v[3]}); return (f32x4){a.x, a.y, b.x, b.y}; }
;     __device__ __forceinline__ void operator()(AccRef acc, const Unit& u, int wr, int wc, int fr, int fq) const {
;     ...
;                     const f32x4 wu0 = *(const f32x4*)(cw + (DFF + jn)), wu1 = *(const f32x4*)(cw + (UPN + DFF + jn)), wu2 = *(const f32x4*)(cw + (2 * UPN + DFF + jn)), bu = *(const f32x4*)(cb + (DFF + jn));
;                     f32x4 pu1 = (f32x4){0.f, 0.f, 0.f, 0.f}, pu2 = pu1;
; #pragma unroll
;                     for (int m = 0; m < 4; ++m) {
;                         const f32x4 au = unpack4(pa[ai][1][m][n]);
;                         const f32x4 ru1 = ror1v(au), ru2 = ror2v(au);
;                         const f32x4 u1 = fr >= 1 ? ru1 : pu1, u2 = fr >= 2 ? ru2 : pu2;
;                         if (m == 0 && fr < 2) *(f32x4*)(edge + (unsigned)((grp * 4 + fr) * UPN + DFF + jn)) = au;
;                         if (m == 3 && fr >= 14) *(f32x4*)(edge + (unsigned)((grp * 4 + (fr - 12)) * UPN + DFF + jn)) = au;
;                         cu[m] = bu + wu0 * u2 + wu1 * u1 + wu2 * au;
;                         pu1 = ru1; pu2 = ru2; }
;                 }
;                 {
;                     const f32x4 wg0 = *(const f32x4*)(cw + jn), wg1 = *(const f32x4*)(cw + (UPN + jn)), wg2 = *(const f32x4*)(cw + (2 * UPN + jn)), bg = *(const f32x4*)(cb + jn);
;                     f32x4 pg1 = (f32x4){0.f, 0.f, 0.f, 0.f}, pg2 = pg1;
; #pragma unroll
;                     for (int m = 0; m < 4; ++m) { const int row = rowg + m * 16 + fr;
;                         const f32x4 ag = unpack4(pa[ai][0][m][n]);
;                         const f32x4 rg1 = ror1v(ag), rg2 = ror2v(ag);
;                         const f32x4 g1 = fr >= 1 ? rg1 : pg1, g2 = fr >= 2 ? rg2 : pg2;
;                         if (m == 0 && fr < 2) *(f32x4*)(edge + (unsigned)((grp * 4 + fr) * UPN + jn)) = ag;
;                         if (m == 3 && fr >= 14) *(f32x4*)(edge + (unsigned)((grp * 4 + (fr - 12)) * UPN + jn)) = ag;
;                         const f32x4 o = gelu4(bg + wg0 * g2 + wg1 * g1 + wg2 * ag) * cu[m];
;                         if (!(m == 0 && fr < 2)) *(u32x2*)(act + (unsigned)(row * DFF + jn)) = pack4(o);
;                         pg1 = rg1; pg2 = rg2; }
.LBB0_567:
	s_or_b64 exec, exec, s[0:1]
	s_nop 0
	v_cndmask_b32_e64 v41, v202, v201, s[6:7]
	v_cndmask_b32_e64 v40, v200, v199, s[6:7]
	v_cndmask_b32_e64 v43, v198, v196, s[6:7]
	v_cndmask_b32_e64 v42, v192, v190, s[6:7]
	v_cndmask_b32_e64 v37, v194, v193, s[8:9]
	v_cndmask_b32_e64 v36, v188, v187, s[8:9]
	v_cndmask_b32_e64 v39, v197, v195, s[8:9]
	v_cndmask_b32_e64 v38, v191, v189, s[8:9]
	s_waitcnt vmcnt(4)
	v_pk_fma_f32 v[42:43], v[8:9], v[42:43], v[12:13]
	v_pk_fma_f32 v[40:41], v[10:11], v[40:41], v[14:15]
	v_pk_fma_f32 v[36:37], v[0:1], v[36:37], v[42:43]
	v_pk_fma_f32 v[38:39], v[2:3], v[38:39], v[40:41]
	v_pk_fma_f32 v[36:37], v[4:5], v[82:83], v[36:37]
	v_pk_fma_f32 v[38:39], v[6:7], v[80:81], v[38:39]
	v_cndmask_b32_e64 v81, v201, v178, s[6:7]
	v_cndmask_b32_e64 v80, v199, v177, s[6:7]
	v_cndmask_b32_e64 v83, v196, v175, s[6:7]
	v_cndmask_b32_e64 v82, v190, v172, s[6:7]
	v_cndmask_b32_e64 v41, v193, v173, s[8:9]
	v_cndmask_b32_e64 v40, v187, v170, s[8:9]
	v_cndmask_b32_e64 v43, v195, v174, s[8:9]
	v_cndmask_b32_e64 v42, v189, v171, s[8:9]
	v_pk_fma_f32 v[82:83], v[8:9], v[82:83], v[12:13]
	v_pk_fma_f32 v[80:81], v[10:11], v[80:81], v[14:15]
	v_pk_fma_f32 v[40:41], v[0:1], v[40:41], v[82:83]
	v_pk_fma_f32 v[42:43], v[2:3], v[42:43], v[80:81]
	v_pk_fma_f32 v[80:81], v[4:5], v[78:79], v[40:41]
	v_pk_fma_f32 v[82:83], v[6:7], v[76:77], v[42:43]
	v_lshlrev_b32_e32 v40, 16, v167
	v_and_b32_e32 v41, 0xffff0000, v167
	v_lshlrev_b32_e32 v42, 16, v149
	v_and_b32_e32 v43, 0xffff0000, v149
	s_nop 1
	v_mov_b32_dpp v146, v40 row_ror:1 row_mask:0xf bank_mask:0xf
	v_mov_b32_dpp v149, v41 row_ror:1 row_mask:0xf bank_mask:0xf
	v_mov_b32_dpp v168, v40 row_ror:2 row_mask:0xf bank_mask:0xf
	v_mov_b32_dpp v169, v41 row_ror:2 row_mask:0xf bank_mask:0xf
	v_cndmask_b32_e64 v79, v85, v149, s[8:9]
	v_cndmask_b32_e64 v78, v84, v146, s[8:9]
	v_cndmask_b32_e64 v85, v89, v169, s[6:7]
	v_cndmask_b32_e64 v84, v88, v168, s[6:7]
	s_waitcnt vmcnt(2)
	v_pk_fma_f32 v[84:85], v[20:21], v[84:85], v[32:33]
	s_nop 1
	v_pk_fma_f32 v[78:79], v[28:29], v[78:79], v[84:85]
	s_nop 1
	v_pk_fma_f32 v[40:41], v[24:25], v[40:41], v[78:79]
	s_nop 1
	v_and_b32_e32 v85, 0x7fffffff, v41
	v_and_b32_e32 v84, 0x7fffffff, v40
	s_nop 1
	v_pk_fma_f32 v[84:85], v[84:85], s[42:43], 1.0 op_sel_hi:[1,0,0]
	v_mov_b32_dpp v152, v42 row_ror:1 row_mask:0xf bank_mask:0xf
	v_mov_b32_dpp v167, v43 row_ror:1 row_mask:0xf bank_mask:0xf
	v_mov_b32_dpp v187, v42 row_ror:2 row_mask:0xf bank_mask:0xf
	v_mov_b32_dpp v188, v43 row_ror:2 row_mask:0xf bank_mask:0xf
	v_rcp_f32_e32 v84, v84
	v_rcp_f32_e32 v85, v85
	v_cndmask_b32_e64 v77, v87, v167, s[8:9]
	v_cndmask_b32_e64 v76, v86, v152, s[8:9]
	v_cndmask_b32_e64 v87, v91, v188, s[6:7]
	v_cndmask_b32_e64 v86, v90, v187, s[6:7]
	v_pk_fma_f32 v[86:87], v[22:23], v[86:87], v[34:35]
	v_pk_mul_f32 v[78:79], v[40:41], v[40:41]
	v_pk_fma_f32 v[76:77], v[30:31], v[76:77], v[86:87]
	v_mov_b64_e32 v[86:87], s[54:55]
	v_pk_mul_f32 v[78:79], v[78:79], s[38:39] op_sel_hi:[1,0]
	v_pk_fma_f32 v[88:89], v[84:85], s[52:53], v[86:87] op_sel_hi:[1,0,0]
	v_exp_f32_e32 v78, v78
	v_exp_f32_e32 v79, v79
	v_pk_fma_f32 v[88:89], v[84:85], v[88:89], s[56:57] op_sel_hi:[1,1,0]
	v_cmp_gt_f32_e64 s[0:1], 0, v40
	v_pk_fma_f32 v[88:89], v[84:85], v[88:89], s[62:63] op_sel_hi:[1,1,0]
	v_pk_fma_f32 v[42:43], v[26:27], v[42:43], v[76:77]
	v_pk_fma_f32 v[88:89], v[84:85], v[88:89], s[64:65] op_sel_hi:[1,1,0]
	v_pk_mul_f32 v[76:77], v[42:43], v[42:43]
	v_pk_mul_f32 v[84:85], v[84:85], v[88:89]
	v_pk_mul_f32 v[76:77], v[76:77], s[38:39] op_sel_hi:[1,0]
	v_pk_mul_f32 v[78:79], v[78:79], v[84:85]
	v_exp_f32_e32 v76, v76
	v_pk_mul_f32 v[84:85], v[40:41], v[78:79]
	v_pk_fma_f32 v[78:79], v[40:41], v[78:79], v[40:41] neg_lo:[1,0,0] neg_hi:[1,0,0]
	v_exp_f32_e32 v77, v77
	v_cndmask_b32_e64 v40, v78, v84, s[0:1]
	v_cmp_gt_f32_e64 s[0:1], 0, v41
	v_and_b32_e32 v78, 0x7fffffff, v42
	v_add_u32_e32 v136, v45, v50
	v_cndmask_b32_e64 v41, v79, v85, s[0:1]
	v_and_b32_e32 v79, 0x7fffffff, v43
	v_pk_fma_f32 v[78:79], v[78:79], s[42:43], 1.0 op_sel_hi:[1,0,0]
	v_cmp_gt_f32_e64 s[0:1], 0, v42
	v_rcp_f32_e32 v78, v78
	v_rcp_f32_e32 v79, v79
	v_pk_mul_f32 v[36:37], v[36:37], v[40:41]
	s_nop 1
	v_cvt_pk_bf16_f32 v36, v36, v37
	v_pk_fma_f32 v[84:85], v[78:79], s[52:53], v[86:87] op_sel_hi:[1,0,0]
	s_nop 1
	v_pk_fma_f32 v[84:85], v[78:79], v[84:85], s[56:57] op_sel_hi:[1,1,0]
	s_nop 1
	v_pk_fma_f32 v[84:85], v[78:79], v[84:85], s[62:63] op_sel_hi:[1,1,0]
	s_nop 0
	v_pk_fma_f32 v[84:85], v[78:79], v[84:85], s[64:65] op_sel_hi:[1,1,0]
	s_nop 0
	v_pk_mul_f32 v[78:79], v[78:79], v[84:85]
	s_nop 0
	v_pk_mul_f32 v[76:77], v[76:77], v[78:79]
	s_nop 0
	v_pk_mul_f32 v[78:79], v[42:43], v[76:77]
	v_pk_fma_f32 v[76:77], v[42:43], v[76:77], v[42:43] neg_lo:[1,0,0] neg_hi:[1,0,0]
	s_nop 0
; __device__ __forceinline__ f32x4 gelu4(f32x4 v) { const f32x2 a = gelu_pk((f32x2){v[0], v[1]}), b = gelu_pk((f32x2){v[2], v[3]}); return (f32x4){a.x, a.y, b.x, b.y}; }
; __device__ __forceinline__ f32x4 ror1v(f32x4 v) { return (f32x4){dpp_ror1(v[0]), dpp_ror1(v[1]), dpp_ror1(v[2]), dpp_ror1(v[3])}; }
; __device__ __forceinline__ f32x4 ror2v(f32x4 v) { return (f32x4){dpp_ror2(v[0]), dpp_ror2(v[1]), dpp_ror2(v[2]), dpp_ror2(v[3])}; }
; __device__ __forceinline__ u32x2 pack4(f32x4 v) { return (u32x2){pk2(v[0], v[1]), pk2(v[2], v[3])}; }
;     __device__ __forceinline__ void operator()(AccRef acc, const Unit& u, int wr, int wc, int fr, int fq) const {
;     ...
;                         const f32x4 au = unpack4(pa[ai][1][m][n]);
;                         const f32x4 ru1 = ror1v(au), ru2 = ror2v(au);
;                         const f32x4 u1 = fr >= 1 ? ru1 : pu1, u2 = fr >= 2 ? ru2 : pu2;
;                         if (m == 0 && fr < 2) *(f32x4*)(edge + (unsigned)((grp * 4 + fr) * UPN + DFF + jn)) = au;
;                         if (m == 3 && fr >= 14) *(f32x4*)(edge + (unsigned)((grp * 4 + (fr - 12)) * UPN + DFF + jn)) = au;
;                         cu[m] = bu + wu0 * u2 + wu1 * u1 + wu2 * au;
;                         pu1 = ru1; pu2 = ru2; }
;                 }
;                 {
;                     const f32x4 wg0 = *(const f32x4*)(cw + jn), wg1 = *(const f32x4*)(cw + (UPN + jn)), wg2 = *(const f32x4*)(cw + (2 * UPN + jn)), bg = *(const f32x4*)(cb + jn);
;                     f32x4 pg1 = (f32x4){0.f, 0.f, 0.f, 0.f}, pg2 = pg1;
; #pragma unroll
;                     for (int m = 0; m < 4; ++m) { const int row = rowg + m * 16 + fr;
;                         const f32x4 ag = unpack4(pa[ai][0][m][n]);
;                         const f32x4 rg1 = ror1v(ag), rg2 = ror2v(ag);
;                         const f32x4 g1 = fr >= 1 ? rg1 : pg1, g2 = fr >= 2 ? rg2 : pg2;
;                         if (m == 0 && fr < 2) *(f32x4*)(edge + (unsigned)((grp * 4 + fr) * UPN + jn)) = ag;
;                         if (m == 3 && fr >= 14) *(f32x4*)(edge + (unsigned)((grp * 4 + (fr - 12)) * UPN + jn)) = ag;
;                         const f32x4 o = gelu4(bg + wg0 * g2 + wg1 * g1 + wg2 * ag) * cu[m];
;                         if (!(m == 0 && fr < 2)) *(u32x2*)(act + (unsigned)(row * DFF + jn)) = pack4(o);
;                         pg1 = rg1; pg2 = rg2; }
	v_cndmask_b32_e64 v42, v76, v78, s[0:1]
	v_cmp_gt_f32_e64 s[0:1], 0, v43
	s_nop 1
	v_cndmask_b32_e64 v43, v77, v79, s[0:1]
	v_pk_mul_f32 v[38:39], v[38:39], v[42:43]
	s_nop 1
	v_cvt_pk_bf16_f32 v37, v38, v39
	v_lshl_add_u64 v[38:39], v[136:137], 1, s[26:27]
	global_store_dwordx2 v[38:39], v[36:37], off
	v_lshlrev_b32_e32 v36, 16, v127
	v_and_b32_e32 v37, 0xffff0000, v127
	s_nop 1
	v_mov_b32_dpp v43, v36 row_ror:2 row_mask:0xf bank_mask:0xf
	v_mov_b32_dpp v40, v36 row_ror:1 row_mask:0xf bank_mask:0xf
	v_mov_b32_dpp v77, v37 row_ror:2 row_mask:0xf bank_mask:0xf
	v_mov_b32_dpp v41, v37 row_ror:1 row_mask:0xf bank_mask:0xf
	v_cndmask_b32_e64 v91, v169, v77, s[6:7]
	v_cndmask_b32_e64 v90, v168, v43, s[6:7]
	v_cndmask_b32_e64 v89, v149, v41, s[8:9]
	v_cndmask_b32_e64 v88, v146, v40, s[8:9]
	v_pk_fma_f32 v[90:91], v[20:21], v[90:91], v[32:33]
	v_lshlrev_b32_e32 v38, 16, v147
	v_pk_fma_f32 v[88:89], v[28:29], v[88:89], v[90:91]
	v_and_b32_e32 v39, 0xffff0000, v147
	v_pk_fma_f32 v[36:37], v[24:25], v[36:37], v[88:89]
	s_nop 1
	v_and_b32_e32 v91, 0x7fffffff, v37
	v_and_b32_e32 v90, 0x7fffffff, v36
	v_pk_fma_f32 v[90:91], v[90:91], s[42:43], 1.0 op_sel_hi:[1,0,0]
	v_mov_b32_dpp v45, v38 row_ror:2 row_mask:0xf bank_mask:0xf
	v_rcp_f32_e32 v90, v90
	v_rcp_f32_e32 v91, v91
	v_mov_b32_dpp v78, v39 row_ror:2 row_mask:0xf bank_mask:0xf
	v_mov_b32_dpp v42, v38 row_ror:1 row_mask:0xf bank_mask:0xf
	v_mov_b32_dpp v76, v39 row_ror:1 row_mask:0xf bank_mask:0xf
	v_cndmask_b32_e64 v147, v188, v78, s[6:7]
	v_cndmask_b32_e64 v146, v187, v45, s[6:7]
	v_cndmask_b32_e64 v85, v167, v76, s[8:9]
	v_cndmask_b32_e64 v84, v152, v42, s[8:9]
	v_pk_fma_f32 v[146:147], v[22:23], v[146:147], v[34:35]
	v_pk_mul_f32 v[88:89], v[36:37], v[36:37]
	v_pk_fma_f32 v[84:85], v[30:31], v[84:85], v[146:147]
	v_pk_mul_f32 v[88:89], v[88:89], s[38:39] op_sel_hi:[1,0]
	v_pk_fma_f32 v[146:147], v[90:91], s[52:53], v[86:87] op_sel_hi:[1,0,0]
	v_exp_f32_e32 v88, v88
	v_exp_f32_e32 v89, v89
	v_pk_fma_f32 v[146:147], v[90:91], v[146:147], s[56:57] op_sel_hi:[1,1,0]
	v_cmp_gt_f32_e64 s[0:1], 0, v36
	v_pk_fma_f32 v[146:147], v[90:91], v[146:147], s[62:63] op_sel_hi:[1,1,0]
	v_pk_fma_f32 v[38:39], v[26:27], v[38:39], v[84:85]
	v_pk_fma_f32 v[146:147], v[90:91], v[146:147], s[64:65] op_sel_hi:[1,1,0]
	v_pk_mul_f32 v[84:85], v[38:39], v[38:39]
	v_pk_mul_f32 v[90:91], v[90:91], v[146:147]
	v_pk_mul_f32 v[84:85], v[84:85], s[38:39] op_sel_hi:[1,0]
	v_pk_mul_f32 v[88:89], v[88:89], v[90:91]
	v_exp_f32_e32 v84, v84
	v_pk_mul_f32 v[90:91], v[36:37], v[88:89]
	v_pk_fma_f32 v[88:89], v[36:37], v[88:89], v[36:37] neg_lo:[1,0,0] neg_hi:[1,0,0]
	v_exp_f32_e32 v85, v85
	v_cndmask_b32_e64 v36, v88, v90, s[0:1]
	v_cmp_gt_f32_e64 s[0:1], 0, v37
	v_and_b32_e32 v88, 0x7fffffff, v38
	v_add_u32_e32 v136, v51, v50
	v_cndmask_b32_e64 v37, v89, v91, s[0:1]
	v_and_b32_e32 v89, 0x7fffffff, v39
	v_pk_fma_f32 v[88:89], v[88:89], s[42:43], 1.0 op_sel_hi:[1,0,0]
	v_cmp_gt_f32_e64 s[0:1], 0, v38
	v_rcp_f32_e32 v88, v88
	v_rcp_f32_e32 v89, v89
	v_pk_mul_f32 v[36:37], v[80:81], v[36:37]
	s_nop 1
	v_cvt_pk_bf16_f32 v36, v36, v37
	v_pk_fma_f32 v[86:87], v[88:89], s[52:53], v[86:87] op_sel_hi:[1,0,0]
	s_nop 1
	v_pk_fma_f32 v[86:87], v[88:89], v[86:87], s[56:57] op_sel_hi:[1,1,0]
	s_nop 1
	v_pk_fma_f32 v[86:87], v[88:89], v[86:87], s[62:63] op_sel_hi:[1,1,0]
	s_nop 1
	v_pk_fma_f32 v[86:87], v[88:89], v[86:87], s[64:65] op_sel_hi:[1,1,0]
	s_nop 0
	v_pk_mul_f32 v[86:87], v[88:89], v[86:87]
	s_nop 0
	v_pk_mul_f32 v[84:85], v[84:85], v[86:87]
	s_nop 0
	v_pk_mul_f32 v[86:87], v[38:39], v[84:85]
	v_pk_fma_f32 v[84:85], v[38:39], v[84:85], v[38:39] neg_lo:[1,0,0] neg_hi:[1,0,0]
	s_nop 0
	v_cndmask_b32_e64 v38, v84, v86, s[0:1]
	v_cmp_gt_f32_e64 s[0:1], 0, v39
	s_nop 1
	s_nop 0
	v_cndmask_b32_e64 v39, v85, v87, s[0:1]
	v_pk_mul_f32 v[38:39], v[82:83], v[38:39]
	s_nop 1
	v_cvt_pk_bf16_f32 v37, v38, v39
	v_lshl_add_u64 v[38:39], v[136:137], 1, s[26:27]
	global_store_dwordx2 v[38:39], v[36:37], off
	v_lshlrev_b32_e32 v36, 16, v124
	v_and_b32_e32 v37, 0xffff0000, v124
	v_lshlrev_b32_e32 v38, 16, v125
	v_and_b32_e32 v39, 0xffff0000, v125
	s_nop 1
	v_mov_b32_dpp v51, v36 row_ror:1 row_mask:0xf bank_mask:0xf
	v_mov_b32_dpp v79, v37 row_ror:1 row_mask:0xf bank_mask:0xf
	v_mov_b32_dpp v80, v38 row_ror:1 row_mask:0xf bank_mask:0xf
	v_mov_b32_dpp v83, v39 row_ror:1 row_mask:0xf bank_mask:0xf
	v_mov_b32_dpp v81, v36 row_ror:2 row_mask:0xf bank_mask:0xf
	v_mov_b32_dpp v84, v37 row_ror:2 row_mask:0xf bank_mask:0xf
	v_mov_b32_dpp v82, v38 row_ror:2 row_mask:0xf bank_mask:0xf
	v_mov_b32_dpp v85, v39 row_ror:2 row_mask:0xf bank_mask:0xf
	s_and_saveexec_b64 s[0:1], vcc
	s_cbranch_execz .LBB0_569
	v_add_u32_e32 v136, v50, v150
	v_lshl_add_u64 v[86:87], v[136:137], 2, s[28:29]
	global_store_dwordx4 v[86:87], v[36:39], off

; __device__ __forceinline__ f32x4 gelu4(f32x4 v) { const f32x2 a = gelu_pk((f32x2){v[0], v[1]}), b = gelu_pk((f32x2){v[2], v[3]}); return (f32x4){a.x, a.y, b.x, b.y}; }
;     __device__ __forceinline__ void operator()(AccRef acc, const Unit& u, int wr, int wc, int fr, int fq) const {
;     ...
;                     const f32x4 wu0 = *(const f32x4*)(cw + (DFF + jn)), wu1 = *(const f32x4*)(cw + (UPN + DFF + jn)), wu2 = *(const f32x4*)(cw + (2 * UPN + DFF + jn)), bu = *(const f32x4*)(cb + (DFF + jn));
;                     f32x4 pu1 = (f32x4){0.f, 0.f, 0.f, 0.f}, pu2 = pu1;
; #pragma unroll
;                     for (int m = 0; m < 4; ++m) {
;                         const f32x4 au = unpack4(pa[ai][1][m][n]);
;                         const f32x4 ru1 = ror1v(au), ru2 = ror2v(au);
;                         const f32x4 u1 = fr >= 1 ? ru1 : pu1, u2 = fr >= 2 ? ru2 : pu2;
;                         if (m == 0 && fr < 2) *(f32x4*)(edge + (unsigned)((grp * 4 + fr) * UPN + DFF + jn)) = au;
;                         if (m == 3 && fr >= 14) *(f32x4*)(edge + (unsigned)((grp * 4 + (fr - 12)) * UPN + DFF + jn)) = au;
;                         cu[m] = bu + wu0 * u2 + wu1 * u1 + wu2 * au;
;                         pu1 = ru1; pu2 = ru2; }
;                 }
;                 {
;                     const f32x4 wg0 = *(const f32x4*)(cw + jn), wg1 = *(const f32x4*)(cw + (UPN + jn)), wg2 = *(const f32x4*)(cw + (2 * UPN + jn)), bg = *(const f32x4*)(cb + jn);
;                     f32x4 pg1 = (f32x4){0.f, 0.f, 0.f, 0.f}, pg2 = pg1;
; #pragma unroll
;                     for (int m = 0; m < 4; ++m) { const int row = rowg + m * 16 + fr;
;                         const f32x4 ag = unpack4(pa[ai][0][m][n]);
;                         const f32x4 rg1 = ror1v(ag), rg2 = ror2v(ag);
;                         const f32x4 g1 = fr >= 1 ? rg1 : pg1, g2 = fr >= 2 ? rg2 : pg2;
;                         if (m == 0 && fr < 2) *(f32x4*)(edge + (unsigned)((grp * 4 + fr) * UPN + jn)) = ag;
;                         if (m == 3 && fr >= 14) *(f32x4*)(edge + (unsigned)((grp * 4 + (fr - 12)) * UPN + jn)) = ag;
;                         const f32x4 o = gelu4(bg + wg0 * g2 + wg1 * g1 + wg2 * ag) * cu[m];
;                         if (!(m == 0 && fr < 2)) *(u32x2*)(act + (unsigned)(row * DFF + jn)) = pack4(o);
;                         pg1 = rg1; pg2 = rg2; }
.LBB0_577:
	s_or_b64 exec, exec, s[0:1]
	s_nop 0
	v_cndmask_b32_e64 v41, v171, v172, s[6:7]
	v_cndmask_b32_e64 v40, v169, v170, s[6:7]
	v_cndmask_b32_e64 v43, v150, v168, s[6:7]
	v_cndmask_b32_e64 v42, v127, v148, s[6:7]
	v_cndmask_b32_e64 v37, v146, v152, s[8:9]
	v_cndmask_b32_e64 v36, v124, v126, s[8:9]
	v_cndmask_b32_e64 v39, v149, v167, s[8:9]
	v_cndmask_b32_e64 v38, v125, v147, s[8:9]
	s_waitcnt vmcnt(4)
	v_pk_fma_f32 v[42:43], v[8:9], v[42:43], v[12:13]
	v_pk_fma_f32 v[40:41], v[10:11], v[40:41], v[14:15]
	v_pk_fma_f32 v[36:37], v[4:5], v[36:37], v[42:43]
	v_pk_fma_f32 v[38:39], v[6:7], v[38:39], v[40:41]
	v_pk_fma_f32 v[36:37], v[0:1], v[58:59], v[36:37]
	v_pk_fma_f32 v[38:39], v[2:3], v[56:57], v[38:39]
	v_cndmask_b32_e64 v57, v172, v90, s[6:7]
	v_cndmask_b32_e64 v56, v170, v89, s[6:7]
	v_cndmask_b32_e64 v59, v168, v88, s[6:7]
	v_cndmask_b32_e64 v58, v148, v85, s[6:7]
	v_cndmask_b32_e64 v41, v152, v86, s[8:9]
	v_cndmask_b32_e64 v40, v126, v83, s[8:9]
	v_cndmask_b32_e64 v43, v167, v87, s[8:9]
	v_cndmask_b32_e64 v42, v147, v84, s[8:9]
	v_pk_fma_f32 v[58:59], v[8:9], v[58:59], v[12:13]
	v_pk_fma_f32 v[56:57], v[10:11], v[56:57], v[14:15]
	v_pk_fma_f32 v[40:41], v[4:5], v[40:41], v[58:59]
	v_pk_fma_f32 v[42:43], v[6:7], v[42:43], v[56:57]
	v_pk_fma_f32 v[56:57], v[0:1], v[54:55], v[40:41]
	v_pk_fma_f32 v[58:59], v[2:3], v[52:53], v[42:43]
	v_lshlrev_b32_e32 v40, 16, v112
	v_and_b32_e32 v41, 0xffff0000, v112
	v_lshlrev_b32_e32 v42, 16, v113
	v_and_b32_e32 v43, 0xffff0000, v113
	s_nop 1
	v_mov_b32_dpp v112, v40 row_ror:1 row_mask:0xf bank_mask:0xf
	v_mov_b32_dpp v113, v41 row_ror:1 row_mask:0xf bank_mask:0xf
	v_mov_b32_dpp v123, v40 row_ror:2 row_mask:0xf bank_mask:0xf
	v_mov_b32_dpp v124, v41 row_ror:2 row_mask:0xf bank_mask:0xf
	v_cndmask_b32_e64 v55, v61, v113, s[8:9]
	v_cndmask_b32_e64 v54, v60, v112, s[8:9]
	v_cndmask_b32_e64 v61, v77, v124, s[6:7]
	v_cndmask_b32_e64 v60, v76, v123, s[6:7]
	s_waitcnt vmcnt(2)
	v_pk_fma_f32 v[60:61], v[28:29], v[60:61], v[32:33]
	s_nop 1
	v_pk_fma_f32 v[54:55], v[24:25], v[54:55], v[60:61]
	s_nop 1
	v_pk_fma_f32 v[40:41], v[20:21], v[40:41], v[54:55]
	s_nop 1
	v_and_b32_e32 v61, 0x7fffffff, v41
	v_and_b32_e32 v60, 0x7fffffff, v40
	v_pk_fma_f32 v[60:61], v[60:61], s[42:43], 1.0 op_sel_hi:[1,0,0]
	s_nop 1
	v_rcp_f32_e32 v60, v60
	v_rcp_f32_e32 v61, v61
	v_mov_b32_dpp v114, v42 row_ror:1 row_mask:0xf bank_mask:0xf
	v_mov_b32_dpp v115, v43 row_ror:1 row_mask:0xf bank_mask:0xf
	v_mov_b32_dpp v125, v42 row_ror:2 row_mask:0xf bank_mask:0xf
	v_mov_b32_dpp v126, v43 row_ror:2 row_mask:0xf bank_mask:0xf
	v_cndmask_b32_e64 v53, v65, v115, s[8:9]
	v_cndmask_b32_e64 v52, v64, v114, s[8:9]
	v_cndmask_b32_e64 v65, v79, v126, s[6:7]
	v_cndmask_b32_e64 v64, v78, v125, s[6:7]
	v_pk_fma_f32 v[64:65], v[30:31], v[64:65], v[34:35]
	v_pk_mul_f32 v[54:55], v[40:41], v[40:41]
	v_mov_b64_e32 v[76:77], s[54:55]
	v_pk_fma_f32 v[52:53], v[26:27], v[52:53], v[64:65]
	v_pk_mul_f32 v[54:55], v[54:55], s[38:39] op_sel_hi:[1,0]
	v_pk_fma_f32 v[64:65], v[60:61], s[52:53], v[76:77] op_sel_hi:[1,0,0]
	v_exp_f32_e32 v54, v54
	v_exp_f32_e32 v55, v55
	v_pk_fma_f32 v[64:65], v[60:61], v[64:65], s[56:57] op_sel_hi:[1,1,0]
	v_cmp_gt_f32_e64 s[0:1], 0, v40
	v_pk_fma_f32 v[64:65], v[60:61], v[64:65], s[62:63] op_sel_hi:[1,1,0]
	v_pk_fma_f32 v[42:43], v[22:23], v[42:43], v[52:53]
	v_pk_fma_f32 v[64:65], v[60:61], v[64:65], s[64:65] op_sel_hi:[1,1,0]
	v_pk_mul_f32 v[52:53], v[42:43], v[42:43]
	v_pk_mul_f32 v[60:61], v[60:61], v[64:65]
	v_pk_mul_f32 v[52:53], v[52:53], s[38:39] op_sel_hi:[1,0]
	v_pk_mul_f32 v[54:55], v[54:55], v[60:61]
	v_exp_f32_e32 v52, v52
	v_pk_mul_f32 v[60:61], v[40:41], v[54:55]
	v_pk_fma_f32 v[54:55], v[40:41], v[54:55], v[40:41] neg_lo:[1,0,0] neg_hi:[1,0,0]
	v_exp_f32_e32 v53, v53
	v_cndmask_b32_e64 v40, v54, v60, s[0:1]
	v_cmp_gt_f32_e64 s[0:1], 0, v41
	v_and_b32_e32 v54, 0x7fffffff, v42
	v_add_u32_e32 v64, 0xb000, v82
	v_cndmask_b32_e64 v41, v55, v61, s[0:1]
	v_and_b32_e32 v55, 0x7fffffff, v43
	v_pk_fma_f32 v[54:55], v[54:55], s[42:43], 1.0 op_sel_hi:[1,0,0]
	v_cmp_gt_f32_e64 s[0:1], 0, v42
	v_rcp_f32_e32 v54, v54
	v_rcp_f32_e32 v55, v55
	v_pk_mul_f32 v[36:37], v[36:37], v[40:41]
	v_add_u32_e32 v136, v64, v44
	v_cvt_pk_bf16_f32 v36, v36, v37
	v_pk_fma_f32 v[60:61], v[54:55], s[52:53], v[76:77] op_sel_hi:[1,0,0]
	s_nop 1
	v_pk_fma_f32 v[60:61], v[54:55], v[60:61], s[56:57] op_sel_hi:[1,1,0]
	s_nop 1
	v_pk_fma_f32 v[60:61], v[54:55], v[60:61], s[62:63] op_sel_hi:[1,1,0]
	v_add_u32_e32 v65, 0x16000, v82
	v_pk_fma_f32 v[60:61], v[54:55], v[60:61], s[64:65] op_sel_hi:[1,1,0]
	s_nop 0
	v_pk_mul_f32 v[54:55], v[54:55], v[60:61]
	s_nop 0
	v_pk_mul_f32 v[52:53], v[52:53], v[54:55]
	s_nop 0
	v_pk_mul_f32 v[54:55], v[42:43], v[52:53]
	v_pk_fma_f32 v[52:53], v[42:43], v[52:53], v[42:43] neg_lo:[1,0,0] neg_hi:[1,0,0]
	s_nop 0
; __device__ __forceinline__ f32x4 gelu4(f32x4 v) { const f32x2 a = gelu_pk((f32x2){v[0], v[1]}), b = gelu_pk((f32x2){v[2], v[3]}); return (f32x4){a.x, a.y, b.x, b.y}; }
; __device__ __forceinline__ f32x4 ror1v(f32x4 v) { return (f32x4){dpp_ror1(v[0]), dpp_ror1(v[1]), dpp_ror1(v[2]), dpp_ror1(v[3])}; }
; __device__ __forceinline__ f32x4 ror2v(f32x4 v) { return (f32x4){dpp_ror2(v[0]), dpp_ror2(v[1]), dpp_ror2(v[2]), dpp_ror2(v[3])}; }
; __device__ __forceinline__ u32x2 pack4(f32x4 v) { return (u32x2){pk2(v[0], v[1]), pk2(v[2], v[3])}; }
;     __device__ __forceinline__ void operator()(AccRef acc, const Unit& u, int wr, int wc, int fr, int fq) const {
;     ...
;                         const f32x4 au = unpack4(pa[ai][1][m][n]);
;                         const f32x4 ru1 = ror1v(au), ru2 = ror2v(au);
;                         const f32x4 u1 = fr >= 1 ? ru1 : pu1, u2 = fr >= 2 ? ru2 : pu2;
;                         if (m == 0 && fr < 2) *(f32x4*)(edge + (unsigned)((grp * 4 + fr) * UPN + DFF + jn)) = au;
;                         if (m == 3 && fr >= 14) *(f32x4*)(edge + (unsigned)((grp * 4 + (fr - 12)) * UPN + DFF + jn)) = au;
;                         cu[m] = bu + wu0 * u2 + wu1 * u1 + wu2 * au;
;                         pu1 = ru1; pu2 = ru2; }
;                 }
;                 {
;                     const f32x4 wg0 = *(const f32x4*)(cw + jn), wg1 = *(const f32x4*)(cw + (UPN + jn)), wg2 = *(const f32x4*)(cw + (2 * UPN + jn)), bg = *(const f32x4*)(cb + jn);
;                     f32x4 pg1 = (f32x4){0.f, 0.f, 0.f, 0.f}, pg2 = pg1;
; #pragma unroll
;                     for (int m = 0; m < 4; ++m) { const int row = rowg + m * 16 + fr;
;                         const f32x4 ag = unpack4(pa[ai][0][m][n]);
;                         const f32x4 rg1 = ror1v(ag), rg2 = ror2v(ag);
;                         const f32x4 g1 = fr >= 1 ? rg1 : pg1, g2 = fr >= 2 ? rg2 : pg2;
;                         if (m == 0 && fr < 2) *(f32x4*)(edge + (unsigned)((grp * 4 + fr) * UPN + jn)) = ag;
;                         if (m == 3 && fr >= 14) *(f32x4*)(edge + (unsigned)((grp * 4 + (fr - 12)) * UPN + jn)) = ag;
;                         const f32x4 o = gelu4(bg + wg0 * g2 + wg1 * g1 + wg2 * ag) * cu[m];
;                         if (!(m == 0 && fr < 2)) *(u32x2*)(act + (unsigned)(row * DFF + jn)) = pack4(o);
;                         pg1 = rg1; pg2 = rg2; }
	v_cndmask_b32_e64 v42, v52, v54, s[0:1]
	v_cmp_gt_f32_e64 s[0:1], 0, v43
	s_nop 1
	v_cndmask_b32_e64 v43, v53, v55, s[0:1]
	v_pk_mul_f32 v[38:39], v[38:39], v[42:43]
	s_nop 1
	v_cvt_pk_bf16_f32 v37, v38, v39
	v_lshl_add_u64 v[38:39], v[136:137], 1, s[26:27]
	global_store_dwordx2 v[38:39], v[36:37], off
	v_lshlrev_b32_e32 v36, 16, v110
	v_and_b32_e32 v37, 0xffff0000, v110
	v_lshlrev_b32_e32 v38, 16, v111
	v_mov_b32_dpp v43, v36 row_ror:2 row_mask:0xf bank_mask:0xf
	v_mov_b32_dpp v54, v37 row_ror:2 row_mask:0xf bank_mask:0xf
	v_and_b32_e32 v39, 0xffff0000, v111
	v_mov_b32_dpp v40, v36 row_ror:1 row_mask:0xf bank_mask:0xf
	v_mov_b32_dpp v41, v37 row_ror:1 row_mask:0xf bank_mask:0xf
	v_cndmask_b32_e64 v111, v124, v54, s[6:7]
	v_cndmask_b32_e64 v110, v123, v43, s[6:7]
	v_cndmask_b32_e64 v79, v113, v41, s[8:9]
	v_cndmask_b32_e64 v78, v112, v40, s[8:9]
	v_pk_fma_f32 v[110:111], v[28:29], v[110:111], v[32:33]
	s_nop 1
	v_pk_fma_f32 v[78:79], v[24:25], v[78:79], v[110:111]
	s_nop 1
	v_pk_fma_f32 v[36:37], v[20:21], v[36:37], v[78:79]
	s_nop 1
	v_and_b32_e32 v111, 0x7fffffff, v37
	v_and_b32_e32 v110, 0x7fffffff, v36
	v_pk_fma_f32 v[110:111], v[110:111], s[42:43], 1.0 op_sel_hi:[1,0,0]
	v_mov_b32_dpp v52, v38 row_ror:2 row_mask:0xf bank_mask:0xf
	v_rcp_f32_e32 v110, v110
	v_rcp_f32_e32 v111, v111
	v_mov_b32_dpp v55, v39 row_ror:2 row_mask:0xf bank_mask:0xf
	v_mov_b32_dpp v42, v38 row_ror:1 row_mask:0xf bank_mask:0xf
	v_mov_b32_dpp v53, v39 row_ror:1 row_mask:0xf bank_mask:0xf
	v_cndmask_b32_e64 v113, v126, v55, s[6:7]
	v_cndmask_b32_e64 v112, v125, v52, s[6:7]
	v_cndmask_b32_e64 v61, v115, v53, s[8:9]
	v_cndmask_b32_e64 v60, v114, v42, s[8:9]
	v_pk_fma_f32 v[112:113], v[30:31], v[112:113], v[34:35]
	v_pk_mul_f32 v[78:79], v[36:37], v[36:37]
	v_pk_fma_f32 v[60:61], v[26:27], v[60:61], v[112:113]
	v_pk_mul_f32 v[78:79], v[78:79], s[38:39] op_sel_hi:[1,0]
	v_pk_fma_f32 v[112:113], v[110:111], s[52:53], v[76:77] op_sel_hi:[1,0,0]
	v_exp_f32_e32 v78, v78
	v_exp_f32_e32 v79, v79
	v_pk_fma_f32 v[112:113], v[110:111], v[112:113], s[56:57] op_sel_hi:[1,1,0]
	v_cmp_gt_f32_e64 s[0:1], 0, v36
	v_pk_fma_f32 v[112:113], v[110:111], v[112:113], s[62:63] op_sel_hi:[1,1,0]
	v_pk_fma_f32 v[38:39], v[22:23], v[38:39], v[60:61]
	v_pk_fma_f32 v[112:113], v[110:111], v[112:113], s[64:65] op_sel_hi:[1,1,0]
	v_pk_mul_f32 v[60:61], v[38:39], v[38:39]
	v_pk_mul_f32 v[110:111], v[110:111], v[112:113]
	v_pk_mul_f32 v[60:61], v[60:61], s[38:39] op_sel_hi:[1,0]
	v_pk_mul_f32 v[78:79], v[78:79], v[110:111]
	v_exp_f32_e32 v60, v60
	v_pk_mul_f32 v[110:111], v[36:37], v[78:79]
	v_pk_fma_f32 v[78:79], v[36:37], v[78:79], v[36:37] neg_lo:[1,0,0] neg_hi:[1,0,0]
	v_exp_f32_e32 v61, v61
	v_cndmask_b32_e64 v36, v78, v110, s[0:1]
	v_cmp_gt_f32_e64 s[0:1], 0, v37
	v_and_b32_e32 v78, 0x7fffffff, v38
	v_add_u32_e32 v136, v65, v44
	v_cndmask_b32_e64 v37, v79, v111, s[0:1]
	v_and_b32_e32 v79, 0x7fffffff, v39
	v_pk_fma_f32 v[78:79], v[78:79], s[42:43], 1.0 op_sel_hi:[1,0,0]
	v_cmp_gt_f32_e64 s[0:1], 0, v38
	v_rcp_f32_e32 v78, v78
	v_rcp_f32_e32 v79, v79
	v_pk_mul_f32 v[36:37], v[56:57], v[36:37]
	s_nop 1
	v_cvt_pk_bf16_f32 v36, v36, v37
	v_pk_fma_f32 v[76:77], v[78:79], s[52:53], v[76:77] op_sel_hi:[1,0,0]
	s_nop 1
	v_pk_fma_f32 v[76:77], v[78:79], v[76:77], s[56:57] op_sel_hi:[1,1,0]
	s_nop 0
	v_pk_fma_f32 v[76:77], v[78:79], v[76:77], s[62:63] op_sel_hi:[1,1,0]
	s_nop 0
	v_pk_fma_f32 v[76:77], v[78:79], v[76:77], s[64:65] op_sel_hi:[1,1,0]
	s_nop 0
	v_pk_mul_f32 v[76:77], v[78:79], v[76:77]
	s_nop 0
	v_pk_mul_f32 v[60:61], v[60:61], v[76:77]
	s_nop 0
	v_pk_mul_f32 v[76:77], v[38:39], v[60:61]
	v_pk_fma_f32 v[60:61], v[38:39], v[60:61], v[38:39] neg_lo:[1,0,0] neg_hi:[1,0,0]
	s_nop 0
	v_cndmask_b32_e64 v38, v60, v76, s[0:1]
	v_cmp_gt_f32_e64 s[0:1], 0, v39
	s_nop 1
	v_cndmask_b32_e64 v39, v61, v77, s[0:1]
	v_pk_mul_f32 v[38:39], v[58:59], v[38:39]
	s_nop 1
	v_cvt_pk_bf16_f32 v37, v38, v39
	v_lshl_add_u64 v[38:39], v[136:137], 1, s[26:27]
	global_store_dwordx2 v[38:39], v[36:37], off
	v_lshlrev_b32_e32 v36, 16, v108
	v_and_b32_e32 v37, 0xffff0000, v108
	v_lshlrev_b32_e32 v38, 16, v109
	v_and_b32_e32 v39, 0xffff0000, v109
	s_nop 1
	v_mov_b32_dpp v56, v36 row_ror:1 row_mask:0xf bank_mask:0xf
	v_mov_b32_dpp v57, v37 row_ror:1 row_mask:0xf bank_mask:0xf
	v_mov_b32_dpp v58, v38 row_ror:1 row_mask:0xf bank_mask:0xf
	v_mov_b32_dpp v61, v39 row_ror:1 row_mask:0xf bank_mask:0xf
	v_mov_b32_dpp v59, v36 row_ror:2 row_mask:0xf bank_mask:0xf
	v_mov_b32_dpp v76, v37 row_ror:2 row_mask:0xf bank_mask:0xf
	v_mov_b32_dpp v60, v38 row_ror:2 row_mask:0xf bank_mask:0xf
	v_mov_b32_dpp v77, v39 row_ror:2 row_mask:0xf bank_mask:0xf
	s_and_saveexec_b64 s[0:1], vcc
	s_cbranch_execz .LBB0_579
	v_add_u32_e32 v136, v51, v44
	v_lshl_add_u64 v[78:79], v[136:137], 2, s[28:29]
	global_store_dwordx4 v[78:79], v[36:39], off

; __device__ __forceinline__ f32x4 gelu4(f32x4 v) { const f32x2 a = gelu_pk((f32x2){v[0], v[1]}), b = gelu_pk((f32x2){v[2], v[3]}); return (f32x4){a.x, a.y, b.x, b.y}; }
;     __device__ __forceinline__ void operator()(AccRef acc, const Unit& u, int wr, int wc, int fr, int fq) const {
;     ...
;                     const f32x4 wu0 = *(const f32x4*)(cw + (DFF + jn)), wu1 = *(const f32x4*)(cw + (UPN + DFF + jn)), wu2 = *(const f32x4*)(cw + (2 * UPN + DFF + jn)), bu = *(const f32x4*)(cb + (DFF + jn));
;                     f32x4 pu1 = (f32x4){0.f, 0.f, 0.f, 0.f}, pu2 = pu1;
; #pragma unroll
;                     for (int m = 0; m < 4; ++m) {
;                         const f32x4 au = unpack4(pa[ai][1][m][n]);
;                         const f32x4 ru1 = ror1v(au), ru2 = ror2v(au);
;                         const f32x4 u1 = fr >= 1 ? ru1 : pu1, u2 = fr >= 2 ? ru2 : pu2;
;                         if (m == 0 && fr < 2) *(f32x4*)(edge + (unsigned)((grp * 4 + fr) * UPN + DFF + jn)) = au;
;                         if (m == 3 && fr >= 14) *(f32x4*)(edge + (unsigned)((grp * 4 + (fr - 12)) * UPN + DFF + jn)) = au;
;                         cu[m] = bu + wu0 * u2 + wu1 * u1 + wu2 * au;
;                         pu1 = ru1; pu2 = ru2; }
;                 }
;                 {
;                     const f32x4 wg0 = *(const f32x4*)(cw + jn), wg1 = *(const f32x4*)(cw + (UPN + jn)), wg2 = *(const f32x4*)(cw + (2 * UPN + jn)), bg = *(const f32x4*)(cb + jn);
;                     f32x4 pg1 = (f32x4){0.f, 0.f, 0.f, 0.f}, pg2 = pg1;
; #pragma unroll
;                     for (int m = 0; m < 4; ++m) { const int row = rowg + m * 16 + fr;
;                         const f32x4 ag = unpack4(pa[ai][0][m][n]);
;                         const f32x4 rg1 = ror1v(ag), rg2 = ror2v(ag);
;                         const f32x4 g1 = fr >= 1 ? rg1 : pg1, g2 = fr >= 2 ? rg2 : pg2;
;                         if (m == 0 && fr < 2) *(f32x4*)(edge + (unsigned)((grp * 4 + fr) * UPN + jn)) = ag;
;                         if (m == 3 && fr >= 14) *(f32x4*)(edge + (unsigned)((grp * 4 + (fr - 12)) * UPN + jn)) = ag;
;                         const f32x4 o = gelu4(bg + wg0 * g2 + wg1 * g1 + wg2 * ag) * cu[m];
;                         if (!(m == 0 && fr < 2)) *(u32x2*)(act + (unsigned)(row * DFF + jn)) = pack4(o);
;                         pg1 = rg1; pg2 = rg2; }
.LBB0_587:
	s_or_b64 exec, exec, s[0:1]
	s_nop 0
	v_cndmask_b32_e64 v41, v115, v114, s[6:7]
	v_cndmask_b32_e64 v40, v113, v112, s[6:7]
	v_cndmask_b32_e64 v43, v111, v109, s[6:7]
	v_cndmask_b32_e64 v42, v101, v91, s[6:7]
	v_cndmask_b32_e64 v37, v108, v102, s[8:9]
	v_cndmask_b32_e64 v36, v89, v88, s[8:9]
	v_cndmask_b32_e64 v39, v110, v103, s[8:9]
	v_cndmask_b32_e64 v38, v100, v90, s[8:9]
	s_waitcnt vmcnt(4)
	v_pk_fma_f32 v[42:43], v[8:9], v[42:43], v[12:13]
	v_pk_fma_f32 v[40:41], v[10:11], v[40:41], v[14:15]
	v_pk_fma_f32 v[36:37], v[4:5], v[36:37], v[42:43]
	v_pk_fma_f32 v[38:39], v[6:7], v[38:39], v[40:41]
	v_pk_fma_f32 v[36:37], v[0:1], v[56:57], v[36:37]
	v_pk_fma_f32 v[38:39], v[2:3], v[54:55], v[38:39]
	v_cndmask_b32_e64 v55, v114, v71, s[6:7]
	v_cndmask_b32_e64 v54, v112, v70, s[6:7]
	v_cndmask_b32_e64 v57, v109, v69, s[6:7]
	v_cndmask_b32_e64 v56, v91, v66, s[6:7]
	v_cndmask_b32_e64 v41, v102, v67, s[8:9]
	v_cndmask_b32_e64 v40, v88, v62, s[8:9]
	v_cndmask_b32_e64 v43, v103, v68, s[8:9]
	v_cndmask_b32_e64 v42, v90, v63, s[8:9]
	v_pk_fma_f32 v[56:57], v[8:9], v[56:57], v[12:13]
	v_pk_fma_f32 v[54:55], v[10:11], v[54:55], v[14:15]
	v_pk_fma_f32 v[40:41], v[4:5], v[40:41], v[56:57]
	v_pk_fma_f32 v[42:43], v[6:7], v[42:43], v[54:55]
	v_pk_fma_f32 v[52:53], v[0:1], v[52:53], v[40:41]
	v_pk_fma_f32 v[54:55], v[2:3], v[44:45], v[42:43]
	v_lshlrev_b32_e32 v40, 16, v96
	v_and_b32_e32 v41, 0xffff0000, v96
	v_lshlrev_b32_e32 v42, 16, v97
	v_and_b32_e32 v43, 0xffff0000, v97
	s_nop 1
	v_mov_b32_dpp v74, v42 row_ror:1 row_mask:0xf bank_mask:0xf
	v_mov_b32_dpp v75, v43 row_ror:1 row_mask:0xf bank_mask:0xf
	v_mov_b32_dpp v80, v40 row_ror:2 row_mask:0xf bank_mask:0xf
	v_mov_b32_dpp v81, v41 row_ror:2 row_mask:0xf bank_mask:0xf
	v_mov_b32_dpp v72, v40 row_ror:1 row_mask:0xf bank_mask:0xf
	v_mov_b32_dpp v73, v41 row_ror:1 row_mask:0xf bank_mask:0xf
	v_cndmask_b32_e64 v45, v49, v75, s[8:9]
	v_cndmask_b32_e64 v44, v48, v74, s[8:9]
	v_cndmask_b32_e64 v49, v59, v81, s[6:7]
	v_cndmask_b32_e64 v48, v58, v80, s[6:7]
	v_cndmask_b32_e64 v47, v47, v73, s[8:9]
	v_cndmask_b32_e64 v46, v46, v72, s[8:9]
	s_waitcnt vmcnt(2)
	v_pk_fma_f32 v[48:49], v[28:29], v[48:49], v[32:33]
	s_nop 1
	v_pk_fma_f32 v[46:47], v[24:25], v[46:47], v[48:49]
	s_nop 1
	v_pk_fma_f32 v[40:41], v[20:21], v[40:41], v[46:47]
	v_mov_b32_dpp v82, v42 row_ror:2 row_mask:0xf bank_mask:0xf
	v_and_b32_e32 v49, 0x7fffffff, v41
	v_and_b32_e32 v48, 0x7fffffff, v40
	v_pk_fma_f32 v[48:49], v[48:49], s[42:43], 1.0 op_sel_hi:[1,0,0]
	v_mov_b32_dpp v88, v43 row_ror:2 row_mask:0xf bank_mask:0xf
	v_rcp_f32_e32 v48, v48
	v_rcp_f32_e32 v49, v49
	v_cndmask_b32_e64 v57, v61, v88, s[6:7]
	v_cndmask_b32_e64 v56, v60, v82, s[6:7]
	v_pk_fma_f32 v[56:57], v[30:31], v[56:57], v[34:35]
	v_pk_mul_f32 v[46:47], v[40:41], v[40:41]
	v_pk_fma_f32 v[44:45], v[26:27], v[44:45], v[56:57]
	v_mov_b64_e32 v[56:57], s[54:55]
	v_pk_mul_f32 v[46:47], v[46:47], s[38:39] op_sel_hi:[1,0]
	v_pk_fma_f32 v[58:59], v[48:49], s[52:53], v[56:57] op_sel_hi:[1,0,0]
	v_exp_f32_e32 v46, v46
	v_exp_f32_e32 v47, v47
	v_pk_fma_f32 v[58:59], v[48:49], v[58:59], s[56:57] op_sel_hi:[1,1,0]
	v_cmp_gt_f32_e64 s[0:1], 0, v40
	v_pk_fma_f32 v[58:59], v[48:49], v[58:59], s[62:63] op_sel_hi:[1,1,0]
	v_pk_fma_f32 v[42:43], v[22:23], v[42:43], v[44:45]
	v_pk_fma_f32 v[58:59], v[48:49], v[58:59], s[64:65] op_sel_hi:[1,1,0]
	v_pk_mul_f32 v[44:45], v[42:43], v[42:43]
	v_pk_mul_f32 v[48:49], v[48:49], v[58:59]
	v_pk_mul_f32 v[44:45], v[44:45], s[38:39] op_sel_hi:[1,0]
	v_pk_mul_f32 v[46:47], v[46:47], v[48:49]
	v_exp_f32_e32 v44, v44
	v_pk_mul_f32 v[48:49], v[40:41], v[46:47]
	v_pk_fma_f32 v[46:47], v[40:41], v[46:47], v[40:41] neg_lo:[1,0,0] neg_hi:[1,0,0]
	v_exp_f32_e32 v45, v45
	v_cndmask_b32_e64 v40, v46, v48, s[0:1]
	v_cmp_gt_f32_e64 s[0:1], 0, v41
	v_and_b32_e32 v46, 0x7fffffff, v42
	v_add_u32_e32 v136, v64, v50
	v_cndmask_b32_e64 v41, v47, v49, s[0:1]
	v_and_b32_e32 v47, 0x7fffffff, v43
	v_pk_fma_f32 v[46:47], v[46:47], s[42:43], 1.0 op_sel_hi:[1,0,0]
	v_cmp_gt_f32_e64 s[0:1], 0, v42
	v_rcp_f32_e32 v46, v46
	v_rcp_f32_e32 v47, v47
	v_pk_mul_f32 v[36:37], v[36:37], v[40:41]
	s_nop 1
	v_cvt_pk_bf16_f32 v36, v36, v37
	v_pk_fma_f32 v[48:49], v[46:47], s[52:53], v[56:57] op_sel_hi:[1,0,0]
	s_nop 1
	v_pk_fma_f32 v[48:49], v[46:47], v[48:49], s[56:57] op_sel_hi:[1,1,0]
	s_nop 0
	v_pk_fma_f32 v[48:49], v[46:47], v[48:49], s[62:63] op_sel_hi:[1,1,0]
	s_nop 0
	v_pk_fma_f32 v[48:49], v[46:47], v[48:49], s[64:65] op_sel_hi:[1,1,0]
	s_nop 0
	v_pk_mul_f32 v[46:47], v[46:47], v[48:49]
	s_nop 0
	v_pk_mul_f32 v[44:45], v[44:45], v[46:47]
	s_nop 0
	v_pk_mul_f32 v[46:47], v[42:43], v[44:45]
	v_pk_fma_f32 v[44:45], v[42:43], v[44:45], v[42:43] neg_lo:[1,0,0] neg_hi:[1,0,0]
	s_nop 0
; __device__ __forceinline__ f32x4 gelu4(f32x4 v) { const f32x2 a = gelu_pk((f32x2){v[0], v[1]}), b = gelu_pk((f32x2){v[2], v[3]}); return (f32x4){a.x, a.y, b.x, b.y}; }
; __device__ __forceinline__ f32x4 ror1v(f32x4 v) { return (f32x4){dpp_ror1(v[0]), dpp_ror1(v[1]), dpp_ror1(v[2]), dpp_ror1(v[3])}; }
; __device__ __forceinline__ f32x4 ror2v(f32x4 v) { return (f32x4){dpp_ror2(v[0]), dpp_ror2(v[1]), dpp_ror2(v[2]), dpp_ror2(v[3])}; }
; __device__ __forceinline__ u32x2 pack4(f32x4 v) { return (u32x2){pk2(v[0], v[1]), pk2(v[2], v[3])}; }
;     __device__ __forceinline__ void operator()(AccRef acc, const Unit& u, int wr, int wc, int fr, int fq) const {
;     ...
;                         const f32x4 au = unpack4(pa[ai][1][m][n]);
;                         const f32x4 ru1 = ror1v(au), ru2 = ror2v(au);
;                         const f32x4 u1 = fr >= 1 ? ru1 : pu1, u2 = fr >= 2 ? ru2 : pu2;
;                         if (m == 0 && fr < 2) *(f32x4*)(edge + (unsigned)((grp * 4 + fr) * UPN + DFF + jn)) = au;
;                         if (m == 3 && fr >= 14) *(f32x4*)(edge + (unsigned)((grp * 4 + (fr - 12)) * UPN + DFF + jn)) = au;
;                         cu[m] = bu + wu0 * u2 + wu1 * u1 + wu2 * au;
;                         pu1 = ru1; pu2 = ru2; }
;                 }
;                 {
;                     const f32x4 wg0 = *(const f32x4*)(cw + jn), wg1 = *(const f32x4*)(cw + (UPN + jn)), wg2 = *(const f32x4*)(cw + (2 * UPN + jn)), bg = *(const f32x4*)(cb + jn);
;                     f32x4 pg1 = (f32x4){0.f, 0.f, 0.f, 0.f}, pg2 = pg1;
; #pragma unroll
;                     for (int m = 0; m < 4; ++m) { const int row = rowg + m * 16 + fr;
;                         const f32x4 ag = unpack4(pa[ai][0][m][n]);
;                         const f32x4 rg1 = ror1v(ag), rg2 = ror2v(ag);
;                         const f32x4 g1 = fr >= 1 ? rg1 : pg1, g2 = fr >= 2 ? rg2 : pg2;
;                         if (m == 0 && fr < 2) *(f32x4*)(edge + (unsigned)((grp * 4 + fr) * UPN + jn)) = ag;
;                         if (m == 3 && fr >= 14) *(f32x4*)(edge + (unsigned)((grp * 4 + (fr - 12)) * UPN + jn)) = ag;
;                         const f32x4 o = gelu4(bg + wg0 * g2 + wg1 * g1 + wg2 * ag) * cu[m];
;                         if (!(m == 0 && fr < 2)) *(u32x2*)(act + (unsigned)(row * DFF + jn)) = pack4(o);
;                         pg1 = rg1; pg2 = rg2; }
	v_cndmask_b32_e64 v42, v44, v46, s[0:1]
	v_cmp_gt_f32_e64 s[0:1], 0, v43
	s_nop 1
	v_cndmask_b32_e64 v43, v45, v47, s[0:1]
	v_pk_mul_f32 v[38:39], v[38:39], v[42:43]
	s_nop 1
	v_cvt_pk_bf16_f32 v37, v38, v39
	v_lshl_add_u64 v[38:39], v[136:137], 1, s[26:27]
	global_store_dwordx2 v[38:39], v[36:37], off
	v_lshlrev_b32_e32 v36, 16, v94
	v_and_b32_e32 v37, 0xffff0000, v94
	v_lshlrev_b32_e32 v38, 16, v95
	v_mov_b32_dpp v44, v36 row_ror:2 row_mask:0xf bank_mask:0xf
	v_mov_b32_dpp v46, v37 row_ror:2 row_mask:0xf bank_mask:0xf
	v_mov_b32_dpp v40, v36 row_ror:1 row_mask:0xf bank_mask:0xf
	v_mov_b32_dpp v41, v37 row_ror:1 row_mask:0xf bank_mask:0xf
	v_cndmask_b32_e64 v61, v81, v46, s[6:7]
	v_cndmask_b32_e64 v60, v80, v44, s[6:7]
	v_cndmask_b32_e64 v59, v73, v41, s[8:9]
	v_cndmask_b32_e64 v58, v72, v40, s[8:9]
	v_pk_fma_f32 v[60:61], v[28:29], v[60:61], v[32:33]
	v_and_b32_e32 v39, 0xffff0000, v95
	v_pk_fma_f32 v[58:59], v[24:25], v[58:59], v[60:61]
	s_nop 1
	v_pk_fma_f32 v[36:37], v[20:21], v[36:37], v[58:59]
	s_nop 1
	v_and_b32_e32 v61, 0x7fffffff, v37
	v_and_b32_e32 v60, 0x7fffffff, v36
	v_pk_fma_f32 v[60:61], v[60:61], s[42:43], 1.0 op_sel_hi:[1,0,0]
	s_nop 1
	v_rcp_f32_e32 v60, v60
	v_rcp_f32_e32 v61, v61
	v_mov_b32_dpp v45, v38 row_ror:2 row_mask:0xf bank_mask:0xf
	v_mov_b32_dpp v47, v39 row_ror:2 row_mask:0xf bank_mask:0xf
	v_mov_b32_dpp v42, v38 row_ror:1 row_mask:0xf bank_mask:0xf
	v_mov_b32_dpp v43, v39 row_ror:1 row_mask:0xf bank_mask:0xf
	v_cndmask_b32_e64 v73, v88, v47, s[6:7]
	v_cndmask_b32_e64 v72, v82, v45, s[6:7]
	v_cndmask_b32_e64 v49, v75, v43, s[8:9]
	v_cndmask_b32_e64 v48, v74, v42, s[8:9]
	v_pk_fma_f32 v[72:73], v[30:31], v[72:73], v[34:35]
	v_pk_mul_f32 v[58:59], v[36:37], v[36:37]
	v_pk_fma_f32 v[48:49], v[26:27], v[48:49], v[72:73]
	v_pk_mul_f32 v[58:59], v[58:59], s[38:39] op_sel_hi:[1,0]
	v_pk_fma_f32 v[72:73], v[60:61], s[52:53], v[56:57] op_sel_hi:[1,0,0]
	v_exp_f32_e32 v58, v58
	v_exp_f32_e32 v59, v59
	v_pk_fma_f32 v[72:73], v[60:61], v[72:73], s[56:57] op_sel_hi:[1,1,0]
	v_cmp_gt_f32_e64 s[0:1], 0, v36
	v_pk_fma_f32 v[72:73], v[60:61], v[72:73], s[62:63] op_sel_hi:[1,1,0]
	v_pk_fma_f32 v[38:39], v[22:23], v[38:39], v[48:49]
	v_pk_fma_f32 v[72:73], v[60:61], v[72:73], s[64:65] op_sel_hi:[1,1,0]
	v_pk_mul_f32 v[48:49], v[38:39], v[38:39]
	v_pk_mul_f32 v[60:61], v[60:61], v[72:73]
	v_pk_mul_f32 v[48:49], v[48:49], s[38:39] op_sel_hi:[1,0]
	v_pk_mul_f32 v[58:59], v[58:59], v[60:61]
	v_exp_f32_e32 v48, v48
	v_pk_mul_f32 v[60:61], v[36:37], v[58:59]
	v_pk_fma_f32 v[58:59], v[36:37], v[58:59], v[36:37] neg_lo:[1,0,0] neg_hi:[1,0,0]
	v_exp_f32_e32 v49, v49
	v_cndmask_b32_e64 v36, v58, v60, s[0:1]
	v_cmp_gt_f32_e64 s[0:1], 0, v37
	v_and_b32_e32 v58, 0x7fffffff, v38
	v_add_u32_e32 v136, v65, v50
	v_cndmask_b32_e64 v37, v59, v61, s[0:1]
	v_and_b32_e32 v59, 0x7fffffff, v39
	v_pk_fma_f32 v[58:59], v[58:59], s[42:43], 1.0 op_sel_hi:[1,0,0]
	v_cmp_gt_f32_e64 s[0:1], 0, v38
	v_rcp_f32_e32 v58, v58
	v_rcp_f32_e32 v59, v59
	v_pk_mul_f32 v[36:37], v[52:53], v[36:37]
	s_nop 1
	v_cvt_pk_bf16_f32 v36, v36, v37
	v_pk_fma_f32 v[56:57], v[58:59], s[52:53], v[56:57] op_sel_hi:[1,0,0]
	s_nop 1
	v_pk_fma_f32 v[56:57], v[58:59], v[56:57], s[56:57] op_sel_hi:[1,1,0]
	s_nop 0
	v_pk_fma_f32 v[56:57], v[58:59], v[56:57], s[62:63] op_sel_hi:[1,1,0]
	s_nop 0
	v_pk_fma_f32 v[56:57], v[58:59], v[56:57], s[64:65] op_sel_hi:[1,1,0]
	s_nop 0
	v_pk_mul_f32 v[56:57], v[58:59], v[56:57]
	s_nop 0
	v_pk_mul_f32 v[48:49], v[48:49], v[56:57]
	s_nop 0
	v_pk_mul_f32 v[56:57], v[38:39], v[48:49]
	v_pk_fma_f32 v[48:49], v[38:39], v[48:49], v[38:39] neg_lo:[1,0,0] neg_hi:[1,0,0]
	s_nop 0
	v_cndmask_b32_e64 v38, v48, v56, s[0:1]
	v_cmp_gt_f32_e64 s[0:1], 0, v39
	s_nop 1
	v_cndmask_b32_e64 v39, v49, v57, s[0:1]
	v_pk_mul_f32 v[38:39], v[54:55], v[38:39]
	s_nop 1
	v_cvt_pk_bf16_f32 v37, v38, v39
	v_lshl_add_u64 v[38:39], v[136:137], 1, s[26:27]
	global_store_dwordx2 v[38:39], v[36:37], off
	v_lshlrev_b32_e32 v36, 16, v92
	v_and_b32_e32 v37, 0xffff0000, v92
	v_lshlrev_b32_e32 v38, 16, v93
	v_and_b32_e32 v39, 0xffff0000, v93
	s_nop 1
	v_mov_b32_dpp v48, v36 row_ror:1 row_mask:0xf bank_mask:0xf
	v_mov_b32_dpp v49, v37 row_ror:1 row_mask:0xf bank_mask:0xf
	v_mov_b32_dpp v52, v38 row_ror:1 row_mask:0xf bank_mask:0xf
	v_mov_b32_dpp v53, v39 row_ror:1 row_mask:0xf bank_mask:0xf
	v_mov_b32_dpp v54, v36 row_ror:2 row_mask:0xf bank_mask:0xf
	v_mov_b32_dpp v56, v37 row_ror:2 row_mask:0xf bank_mask:0xf
	v_mov_b32_dpp v55, v38 row_ror:2 row_mask:0xf bank_mask:0xf
	v_mov_b32_dpp v57, v39 row_ror:2 row_mask:0xf bank_mask:0xf
	s_and_saveexec_b64 s[0:1], vcc
	s_cbranch_execz .LBB0_589
	v_add_u32_e32 v136, v50, v51
	v_lshl_add_u64 v[58:59], v[136:137], 2, s[28:29]
	global_store_dwordx4 v[58:59], v[36:39], off

; __device__ __forceinline__ f32x4 gelu4(f32x4 v) { const f32x2 a = gelu_pk((f32x2){v[0], v[1]}), b = gelu_pk((f32x2){v[2], v[3]}); return (f32x4){a.x, a.y, b.x, b.y}; }
;     __device__ __forceinline__ void operator()(AccRef acc, const Unit& u, int wr, int wc, int fr, int fq) const {
;     ...
;                     const f32x4 wu0 = *(const f32x4*)(cw + (DFF + jn)), wu1 = *(const f32x4*)(cw + (UPN + DFF + jn)), wu2 = *(const f32x4*)(cw + (2 * UPN + DFF + jn)), bu = *(const f32x4*)(cb + (DFF + jn));
;                     f32x4 pu1 = (f32x4){0.f, 0.f, 0.f, 0.f}, pu2 = pu1;
; #pragma unroll
;                     for (int m = 0; m < 4; ++m) {
;                         const f32x4 au = unpack4(pa[ai][1][m][n]);
;                         const f32x4 ru1 = ror1v(au), ru2 = ror2v(au);
;                         const f32x4 u1 = fr >= 1 ? ru1 : pu1, u2 = fr >= 2 ? ru2 : pu2;
;                         if (m == 0 && fr < 2) *(f32x4*)(edge + (unsigned)((grp * 4 + fr) * UPN + DFF + jn)) = au;
;                         if (m == 3 && fr >= 14) *(f32x4*)(edge + (unsigned)((grp * 4 + (fr - 12)) * UPN + DFF + jn)) = au;
;                         cu[m] = bu + wu0 * u2 + wu1 * u1 + wu2 * au;
;                         pu1 = ru1; pu2 = ru2; }
;                 }
;                 {
;                     const f32x4 wg0 = *(const f32x4*)(cw + jn), wg1 = *(const f32x4*)(cw + (UPN + jn)), wg2 = *(const f32x4*)(cw + (2 * UPN + jn)), bg = *(const f32x4*)(cb + jn);
;                     f32x4 pg1 = (f32x4){0.f, 0.f, 0.f, 0.f}, pg2 = pg1;
; #pragma unroll
;                     for (int m = 0; m < 4; ++m) { const int row = rowg + m * 16 + fr;
;                         const f32x4 ag = unpack4(pa[ai][0][m][n]);
;                         const f32x4 rg1 = ror1v(ag), rg2 = ror2v(ag);
;                         const f32x4 g1 = fr >= 1 ? rg1 : pg1, g2 = fr >= 2 ? rg2 : pg2;
;                         if (m == 0 && fr < 2) *(f32x4*)(edge + (unsigned)((grp * 4 + fr) * UPN + jn)) = ag;
;                         if (m == 3 && fr >= 14) *(f32x4*)(edge + (unsigned)((grp * 4 + (fr - 12)) * UPN + jn)) = ag;
;                         const f32x4 o = gelu4(bg + wg0 * g2 + wg1 * g1 + wg2 * ag) * cu[m];
;                         if (!(m == 0 && fr < 2)) *(u32x2*)(act + (unsigned)(row * DFF + jn)) = pack4(o);
;                         pg1 = rg1; pg2 = rg2; }
.LBB0_1414:
	s_or_b64 exec, exec, s[0:1]
	s_nop 0
	v_cndmask_b32_e64 v41, v204, v206, s[6:7]
	v_cndmask_b32_e64 v40, v201, v205, s[6:7]
	v_cndmask_b32_e64 v43, v197, v203, s[6:7]
	v_cndmask_b32_e64 v42, v193, v199, s[6:7]
	v_cndmask_b32_e64 v37, v194, v200, s[8:9]
	v_cndmask_b32_e64 v36, v191, v195, s[8:9]
	v_cndmask_b32_e64 v39, v196, v202, s[8:9]
	v_cndmask_b32_e64 v38, v192, v198, s[8:9]
	s_waitcnt vmcnt(4)
	v_pk_fma_f32 v[42:43], v[8:9], v[42:43], v[12:13]
	v_pk_fma_f32 v[40:41], v[10:11], v[40:41], v[14:15]
	v_pk_fma_f32 v[36:37], v[0:1], v[36:37], v[42:43]
	v_pk_fma_f32 v[38:39], v[2:3], v[38:39], v[40:41]
	v_pk_fma_f32 v[36:37], v[4:5], v[68:69], v[36:37]
	v_pk_fma_f32 v[38:39], v[6:7], v[66:67], v[38:39]
	v_cndmask_b32_e64 v67, v206, v180, s[6:7]
	v_cndmask_b32_e64 v66, v205, v179, s[6:7]
	v_cndmask_b32_e64 v69, v203, v178, s[6:7]
	v_cndmask_b32_e64 v68, v199, v87, s[6:7]
	v_cndmask_b32_e64 v41, v200, v95, s[8:9]
	v_cndmask_b32_e64 v40, v195, v85, s[8:9]
	v_cndmask_b32_e64 v43, v202, v177, s[8:9]
	v_cndmask_b32_e64 v42, v198, v86, s[8:9]
	v_pk_fma_f32 v[68:69], v[8:9], v[68:69], v[12:13]
	v_pk_fma_f32 v[66:67], v[10:11], v[66:67], v[14:15]
	v_pk_fma_f32 v[40:41], v[0:1], v[40:41], v[68:69]
	v_pk_fma_f32 v[42:43], v[2:3], v[42:43], v[66:67]
	v_pk_fma_f32 v[66:67], v[4:5], v[60:61], v[40:41]
	v_pk_fma_f32 v[68:69], v[6:7], v[46:47], v[42:43]
	v_lshlrev_b32_e32 v40, 16, v94
	v_and_b32_e32 v41, 0xffff0000, v94
	v_lshlrev_b32_e32 v42, 16, v93
	v_and_b32_e32 v43, 0xffff0000, v93
	s_nop 1
	v_mov_b32_dpp v93, v40 row_ror:1 row_mask:0xf bank_mask:0xf
	v_mov_b32_dpp v94, v41 row_ror:1 row_mask:0xf bank_mask:0xf
	v_mov_b32_dpp v191, v40 row_ror:2 row_mask:0xf bank_mask:0xf
	v_mov_b32_dpp v192, v41 row_ror:2 row_mask:0xf bank_mask:0xf
	v_cndmask_b32_e64 v61, v71, v94, s[8:9]
	v_cndmask_b32_e64 v60, v70, v93, s[8:9]
	v_cndmask_b32_e64 v71, v75, v192, s[6:7]
	v_cndmask_b32_e64 v70, v74, v191, s[6:7]
	s_waitcnt vmcnt(2)
	v_pk_fma_f32 v[70:71], v[28:29], v[70:71], v[32:33]
	s_nop 1
	v_pk_fma_f32 v[60:61], v[20:21], v[60:61], v[70:71]
	s_nop 1
	v_pk_fma_f32 v[40:41], v[24:25], v[40:41], v[60:61]
	s_nop 1
	v_and_b32_e32 v71, 0x7fffffff, v41
	v_and_b32_e32 v70, 0x7fffffff, v40
	s_nop 1
	v_pk_fma_f32 v[70:71], v[70:71], s[52:53], 1.0 op_sel_hi:[1,0,0]
	v_mov_b32_dpp v189, v42 row_ror:1 row_mask:0xf bank_mask:0xf
	v_mov_b32_dpp v190, v43 row_ror:1 row_mask:0xf bank_mask:0xf
	v_mov_b32_dpp v193, v42 row_ror:2 row_mask:0xf bank_mask:0xf
	v_mov_b32_dpp v194, v43 row_ror:2 row_mask:0xf bank_mask:0xf
	v_rcp_f32_e32 v70, v70
	v_rcp_f32_e32 v71, v71
	v_cndmask_b32_e64 v47, v73, v190, s[8:9]
	v_cndmask_b32_e64 v46, v72, v189, s[8:9]
	v_cndmask_b32_e64 v73, v77, v194, s[6:7]
	v_cndmask_b32_e64 v72, v76, v193, s[6:7]
	v_pk_fma_f32 v[72:73], v[30:31], v[72:73], v[34:35]
	v_pk_mul_f32 v[60:61], v[40:41], v[40:41]
	v_pk_fma_f32 v[46:47], v[22:23], v[46:47], v[72:73]
	v_mov_b64_e32 v[72:73], s[56:57]
	v_pk_mul_f32 v[60:61], v[60:61], s[42:43] op_sel_hi:[1,0]
	v_pk_fma_f32 v[74:75], v[70:71], s[54:55], v[72:73] op_sel_hi:[1,0,0]
	v_exp_f32_e32 v60, v60
	v_exp_f32_e32 v61, v61
	v_pk_fma_f32 v[74:75], v[70:71], v[74:75], s[58:59] op_sel_hi:[1,1,0]
	v_cmp_gt_f32_e64 s[0:1], 0, v40
	v_pk_fma_f32 v[74:75], v[70:71], v[74:75], s[60:61] op_sel_hi:[1,1,0]
	v_pk_fma_f32 v[42:43], v[26:27], v[42:43], v[46:47]
	v_pk_fma_f32 v[74:75], v[70:71], v[74:75], s[62:63] op_sel_hi:[1,1,0]
	v_pk_mul_f32 v[46:47], v[42:43], v[42:43]
	v_pk_mul_f32 v[70:71], v[70:71], v[74:75]
	v_pk_mul_f32 v[46:47], v[46:47], s[42:43] op_sel_hi:[1,0]
	v_pk_mul_f32 v[60:61], v[60:61], v[70:71]
	v_exp_f32_e32 v46, v46
	v_pk_mul_f32 v[70:71], v[40:41], v[60:61]
	v_pk_fma_f32 v[60:61], v[40:41], v[60:61], v[40:41] neg_lo:[1,0,0] neg_hi:[1,0,0]
	v_exp_f32_e32 v47, v47
	v_cndmask_b32_e64 v40, v60, v70, s[0:1]
	v_cmp_gt_f32_e64 s[0:1], 0, v41
	v_and_b32_e32 v60, 0x7fffffff, v42
	v_mul_lo_u32 v45, v148, s86
	v_cndmask_b32_e64 v41, v61, v71, s[0:1]
	v_and_b32_e32 v61, 0x7fffffff, v43
	v_pk_fma_f32 v[60:61], v[60:61], s[52:53], 1.0 op_sel_hi:[1,0,0]
	v_cmp_gt_f32_e64 s[0:1], 0, v42
	v_rcp_f32_e32 v60, v60
	v_rcp_f32_e32 v61, v61
	v_pk_mul_f32 v[36:37], v[36:37], v[40:41]
	v_add_u32_e32 v136, v45, v44
	v_cvt_pk_bf16_f32 v36, v36, v37
	v_pk_fma_f32 v[70:71], v[60:61], s[54:55], v[72:73] op_sel_hi:[1,0,0]
	s_nop 1
	v_pk_fma_f32 v[70:71], v[60:61], v[70:71], s[58:59] op_sel_hi:[1,1,0]
	s_nop 1
	v_pk_fma_f32 v[70:71], v[60:61], v[70:71], s[60:61] op_sel_hi:[1,1,0]
	v_add_u32_e32 v148, 0xb000, v45
	v_pk_fma_f32 v[70:71], v[60:61], v[70:71], s[62:63] op_sel_hi:[1,1,0]
	s_nop 0
	v_pk_mul_f32 v[60:61], v[60:61], v[70:71]
	s_nop 0
	v_pk_mul_f32 v[46:47], v[46:47], v[60:61]
	s_nop 0
	v_pk_mul_f32 v[60:61], v[42:43], v[46:47]
	v_pk_fma_f32 v[46:47], v[42:43], v[46:47], v[42:43] neg_lo:[1,0,0] neg_hi:[1,0,0]
; __device__ __forceinline__ f32x4 gelu4(f32x4 v) { const f32x2 a = gelu_pk((f32x2){v[0], v[1]}), b = gelu_pk((f32x2){v[2], v[3]}); return (f32x4){a.x, a.y, b.x, b.y}; }
; __device__ __forceinline__ f32x4 ror1v(f32x4 v) { return (f32x4){dpp_ror1(v[0]), dpp_ror1(v[1]), dpp_ror1(v[2]), dpp_ror1(v[3])}; }
; __device__ __forceinline__ f32x4 ror2v(f32x4 v) { return (f32x4){dpp_ror2(v[0]), dpp_ror2(v[1]), dpp_ror2(v[2]), dpp_ror2(v[3])}; }
; __device__ __forceinline__ u32x2 pack4(f32x4 v) { return (u32x2){pk2(v[0], v[1]), pk2(v[2], v[3])}; }
;     __device__ __forceinline__ void operator()(AccRef acc, const Unit& u, int wr, int wc, int fr, int fq) const {
;     ...
;                         const f32x4 au = unpack4(pa[ai][1][m][n]);
;                         const f32x4 ru1 = ror1v(au), ru2 = ror2v(au);
;                         const f32x4 u1 = fr >= 1 ? ru1 : pu1, u2 = fr >= 2 ? ru2 : pu2;
;                         if (m == 0 && fr < 2) *(f32x4*)(edge + (unsigned)((grp * 4 + fr) * UPN + DFF + jn)) = au;
;                         if (m == 3 && fr >= 14) *(f32x4*)(edge + (unsigned)((grp * 4 + (fr - 12)) * UPN + DFF + jn)) = au;
;                         cu[m] = bu + wu0 * u2 + wu1 * u1 + wu2 * au;
;                         pu1 = ru1; pu2 = ru2; }
;                 }
;                 {
;                     const f32x4 wg0 = *(const f32x4*)(cw + jn), wg1 = *(const f32x4*)(cw + (UPN + jn)), wg2 = *(const f32x4*)(cw + (2 * UPN + jn)), bg = *(const f32x4*)(cb + jn);
;                     f32x4 pg1 = (f32x4){0.f, 0.f, 0.f, 0.f}, pg2 = pg1;
; #pragma unroll
;                     for (int m = 0; m < 4; ++m) { const int row = rowg + m * 16 + fr;
;                         const f32x4 ag = unpack4(pa[ai][0][m][n]);
;                         const f32x4 rg1 = ror1v(ag), rg2 = ror2v(ag);
;                         const f32x4 g1 = fr >= 1 ? rg1 : pg1, g2 = fr >= 2 ? rg2 : pg2;
;                         if (m == 0 && fr < 2) *(f32x4*)(edge + (unsigned)((grp * 4 + fr) * UPN + jn)) = ag;
;                         if (m == 3 && fr >= 14) *(f32x4*)(edge + (unsigned)((grp * 4 + (fr - 12)) * UPN + jn)) = ag;
;                         const f32x4 o = gelu4(bg + wg0 * g2 + wg1 * g1 + wg2 * ag) * cu[m];
;                         if (!(m == 0 && fr < 2)) *(u32x2*)(act + (unsigned)(row * DFF + jn)) = pack4(o);
;                         pg1 = rg1; pg2 = rg2; }
	s_nop 0
	v_cndmask_b32_e64 v42, v46, v60, s[0:1]
	v_cmp_gt_f32_e64 s[0:1], 0, v43
	s_nop 1
	v_cndmask_b32_e64 v43, v47, v61, s[0:1]
	v_pk_mul_f32 v[38:39], v[38:39], v[42:43]
	s_nop 1
	v_cvt_pk_bf16_f32 v37, v38, v39
	v_lshl_add_u64 v[38:39], v[136:137], 1, s[26:27]
	global_store_dwordx2 v[38:39], v[36:37], off
	v_lshlrev_b32_e32 v36, 16, v92
	v_and_b32_e32 v37, 0xffff0000, v92
	v_lshlrev_b32_e32 v38, 16, v91
	v_mov_b32_dpp v43, v36 row_ror:2 row_mask:0xf bank_mask:0xf
	v_mov_b32_dpp v60, v37 row_ror:2 row_mask:0xf bank_mask:0xf
	v_mov_b32_dpp v40, v36 row_ror:1 row_mask:0xf bank_mask:0xf
	v_mov_b32_dpp v41, v37 row_ror:1 row_mask:0xf bank_mask:0xf
	v_cndmask_b32_e64 v77, v192, v60, s[6:7]
	v_cndmask_b32_e64 v76, v191, v43, s[6:7]
	v_cndmask_b32_e64 v75, v94, v41, s[8:9]
	v_cndmask_b32_e64 v74, v93, v40, s[8:9]
	v_pk_fma_f32 v[76:77], v[28:29], v[76:77], v[32:33]
	v_and_b32_e32 v39, 0xffff0000, v91
	v_pk_fma_f32 v[74:75], v[20:21], v[74:75], v[76:77]
	s_nop 1
	v_pk_fma_f32 v[36:37], v[24:25], v[36:37], v[74:75]
	s_nop 1
	v_and_b32_e32 v77, 0x7fffffff, v37
	v_and_b32_e32 v76, 0x7fffffff, v36
	v_pk_fma_f32 v[76:77], v[76:77], s[52:53], 1.0 op_sel_hi:[1,0,0]
	s_nop 1
	v_rcp_f32_e32 v76, v76
	v_rcp_f32_e32 v77, v77
	v_mov_b32_dpp v46, v38 row_ror:2 row_mask:0xf bank_mask:0xf
	v_mov_b32_dpp v61, v39 row_ror:2 row_mask:0xf bank_mask:0xf
	v_mov_b32_dpp v42, v38 row_ror:1 row_mask:0xf bank_mask:0xf
	v_mov_b32_dpp v47, v39 row_ror:1 row_mask:0xf bank_mask:0xf
	v_cndmask_b32_e64 v93, v194, v61, s[6:7]
	v_cndmask_b32_e64 v92, v193, v46, s[6:7]
	v_cndmask_b32_e64 v71, v190, v47, s[8:9]
	v_cndmask_b32_e64 v70, v189, v42, s[8:9]
	v_pk_fma_f32 v[92:93], v[30:31], v[92:93], v[34:35]
	v_pk_mul_f32 v[74:75], v[36:37], v[36:37]
	v_pk_fma_f32 v[70:71], v[22:23], v[70:71], v[92:93]
	v_pk_mul_f32 v[74:75], v[74:75], s[42:43] op_sel_hi:[1,0]
	v_pk_fma_f32 v[92:93], v[76:77], s[54:55], v[72:73] op_sel_hi:[1,0,0]
	v_exp_f32_e32 v74, v74
	v_exp_f32_e32 v75, v75
	v_pk_fma_f32 v[92:93], v[76:77], v[92:93], s[58:59] op_sel_hi:[1,1,0]
	v_cmp_gt_f32_e64 s[0:1], 0, v36
	v_pk_fma_f32 v[92:93], v[76:77], v[92:93], s[60:61] op_sel_hi:[1,1,0]
	v_pk_fma_f32 v[38:39], v[26:27], v[38:39], v[70:71]
	v_pk_fma_f32 v[92:93], v[76:77], v[92:93], s[62:63] op_sel_hi:[1,1,0]
	v_pk_mul_f32 v[70:71], v[38:39], v[38:39]
	v_pk_mul_f32 v[76:77], v[76:77], v[92:93]
	v_pk_mul_f32 v[70:71], v[70:71], s[42:43] op_sel_hi:[1,0]
	v_pk_mul_f32 v[74:75], v[74:75], v[76:77]
	v_exp_f32_e32 v70, v70
	v_pk_mul_f32 v[76:77], v[36:37], v[74:75]
	v_pk_fma_f32 v[74:75], v[36:37], v[74:75], v[36:37] neg_lo:[1,0,0] neg_hi:[1,0,0]
	v_exp_f32_e32 v71, v71
	v_cndmask_b32_e64 v36, v74, v76, s[0:1]
	v_cmp_gt_f32_e64 s[0:1], 0, v37
	v_and_b32_e32 v74, 0x7fffffff, v38
	v_add_u32_e32 v136, v148, v44
	v_cndmask_b32_e64 v37, v75, v77, s[0:1]
	v_and_b32_e32 v75, 0x7fffffff, v39
	v_pk_fma_f32 v[74:75], v[74:75], s[52:53], 1.0 op_sel_hi:[1,0,0]
	v_cmp_gt_f32_e64 s[0:1], 0, v38
	v_rcp_f32_e32 v74, v74
	v_rcp_f32_e32 v75, v75
	v_pk_mul_f32 v[36:37], v[66:67], v[36:37]
	s_nop 1
	v_cvt_pk_bf16_f32 v36, v36, v37
	v_pk_fma_f32 v[72:73], v[74:75], s[54:55], v[72:73] op_sel_hi:[1,0,0]
	s_nop 1
	v_pk_fma_f32 v[72:73], v[74:75], v[72:73], s[58:59] op_sel_hi:[1,1,0]
	s_nop 0
	v_pk_fma_f32 v[72:73], v[74:75], v[72:73], s[60:61] op_sel_hi:[1,1,0]
	s_nop 0
	v_pk_fma_f32 v[72:73], v[74:75], v[72:73], s[62:63] op_sel_hi:[1,1,0]
	s_nop 0
	v_pk_mul_f32 v[72:73], v[74:75], v[72:73]
	s_nop 0
	v_pk_mul_f32 v[70:71], v[70:71], v[72:73]
	s_nop 0
	v_pk_mul_f32 v[72:73], v[38:39], v[70:71]
	v_pk_fma_f32 v[70:71], v[38:39], v[70:71], v[38:39] neg_lo:[1,0,0] neg_hi:[1,0,0]
	s_nop 0
	v_cndmask_b32_e64 v38, v70, v72, s[0:1]
	v_cmp_gt_f32_e64 s[0:1], 0, v39
	s_nop 1
	v_cndmask_b32_e64 v39, v71, v73, s[0:1]
	v_pk_mul_f32 v[38:39], v[68:69], v[38:39]
	s_nop 1
	v_cvt_pk_bf16_f32 v37, v38, v39
	v_lshl_add_u64 v[38:39], v[136:137], 1, s[26:27]
	global_store_dwordx2 v[38:39], v[36:37], off
	v_lshlrev_b32_e32 v36, 16, v82
	v_and_b32_e32 v37, 0xffff0000, v82
	v_lshlrev_b32_e32 v38, 16, v83
	v_and_b32_e32 v39, 0xffff0000, v83
	s_nop 1
	v_mov_b32_dpp v66, v36 row_ror:1 row_mask:0xf bank_mask:0xf
	v_mov_b32_dpp v67, v37 row_ror:1 row_mask:0xf bank_mask:0xf
	v_mov_b32_dpp v68, v38 row_ror:1 row_mask:0xf bank_mask:0xf
	v_mov_b32_dpp v71, v39 row_ror:1 row_mask:0xf bank_mask:0xf
	v_mov_b32_dpp v69, v36 row_ror:2 row_mask:0xf bank_mask:0xf
	v_mov_b32_dpp v72, v37 row_ror:2 row_mask:0xf bank_mask:0xf
	v_mov_b32_dpp v70, v38 row_ror:2 row_mask:0xf bank_mask:0xf
	v_mov_b32_dpp v73, v39 row_ror:2 row_mask:0xf bank_mask:0xf
	s_and_saveexec_b64 s[0:1], vcc
	s_cbranch_execz .LBB0_1416
	v_add_u32_e32 v136, v152, v44
	v_lshl_add_u64 v[74:75], v[136:137], 2, s[28:29]
	global_store_dwordx4 v[74:75], v[36:39], off

; __device__ __forceinline__ f32x4 gelu4(f32x4 v) { const f32x2 a = gelu_pk((f32x2){v[0], v[1]}), b = gelu_pk((f32x2){v[2], v[3]}); return (f32x4){a.x, a.y, b.x, b.y}; }
;     __device__ __forceinline__ void operator()(AccRef acc, const Unit& u, int wr, int wc, int fr, int fq) const {
;     ...
;                     const f32x4 wu0 = *(const f32x4*)(cw + (DFF + jn)), wu1 = *(const f32x4*)(cw + (UPN + DFF + jn)), wu2 = *(const f32x4*)(cw + (2 * UPN + DFF + jn)), bu = *(const f32x4*)(cb + (DFF + jn));
;                     f32x4 pu1 = (f32x4){0.f, 0.f, 0.f, 0.f}, pu2 = pu1;
; #pragma unroll
;                     for (int m = 0; m < 4; ++m) {
;                         const f32x4 au = unpack4(pa[ai][1][m][n]);
;                         const f32x4 ru1 = ror1v(au), ru2 = ror2v(au);
;                         const f32x4 u1 = fr >= 1 ? ru1 : pu1, u2 = fr >= 2 ? ru2 : pu2;
;                         if (m == 0 && fr < 2) *(f32x4*)(edge + (unsigned)((grp * 4 + fr) * UPN + DFF + jn)) = au;
;                         if (m == 3 && fr >= 14) *(f32x4*)(edge + (unsigned)((grp * 4 + (fr - 12)) * UPN + DFF + jn)) = au;
;                         cu[m] = bu + wu0 * u2 + wu1 * u1 + wu2 * au;
;                         pu1 = ru1; pu2 = ru2; }
;                 }
;                 {
;                     const f32x4 wg0 = *(const f32x4*)(cw + jn), wg1 = *(const f32x4*)(cw + (UPN + jn)), wg2 = *(const f32x4*)(cw + (2 * UPN + jn)), bg = *(const f32x4*)(cb + jn);
;                     f32x4 pg1 = (f32x4){0.f, 0.f, 0.f, 0.f}, pg2 = pg1;
; #pragma unroll
;                     for (int m = 0; m < 4; ++m) { const int row = rowg + m * 16 + fr;
;                         const f32x4 ag = unpack4(pa[ai][0][m][n]);
;                         const f32x4 rg1 = ror1v(ag), rg2 = ror2v(ag);
;                         const f32x4 g1 = fr >= 1 ? rg1 : pg1, g2 = fr >= 2 ? rg2 : pg2;
;                         if (m == 0 && fr < 2) *(f32x4*)(edge + (unsigned)((grp * 4 + fr) * UPN + jn)) = ag;
;                         if (m == 3 && fr >= 14) *(f32x4*)(edge + (unsigned)((grp * 4 + (fr - 12)) * UPN + jn)) = ag;
;                         const f32x4 o = gelu4(bg + wg0 * g2 + wg1 * g1 + wg2 * ag) * cu[m];
;                         if (!(m == 0 && fr < 2)) *(u32x2*)(act + (unsigned)(row * DFF + jn)) = pack4(o);
;                         pg1 = rg1; pg2 = rg2; }
.LBB0_1424:
	s_or_b64 exec, exec, s[0:1]
	s_nop 0
	v_cndmask_b32_e64 v41, v207, v206, s[6:7]
	v_cndmask_b32_e64 v40, v205, v204, s[6:7]
	v_cndmask_b32_e64 v43, v203, v201, s[6:7]
	v_cndmask_b32_e64 v42, v197, v195, s[6:7]
	v_cndmask_b32_e64 v37, v199, v198, s[8:9]
	v_cndmask_b32_e64 v36, v193, v192, s[8:9]
	v_cndmask_b32_e64 v39, v202, v200, s[8:9]
	v_cndmask_b32_e64 v38, v196, v194, s[8:9]
	s_waitcnt vmcnt(4)
	v_pk_fma_f32 v[42:43], v[8:9], v[42:43], v[12:13]
	v_pk_fma_f32 v[40:41], v[10:11], v[40:41], v[14:15]
	v_pk_fma_f32 v[36:37], v[0:1], v[36:37], v[42:43]
	v_pk_fma_f32 v[38:39], v[2:3], v[38:39], v[40:41]
	v_pk_fma_f32 v[36:37], v[4:5], v[86:87], v[36:37]
	v_pk_fma_f32 v[38:39], v[6:7], v[84:85], v[38:39]
	v_cndmask_b32_e64 v85, v206, v183, s[6:7]
	v_cndmask_b32_e64 v84, v204, v182, s[6:7]
	v_cndmask_b32_e64 v87, v201, v181, s[6:7]
	v_cndmask_b32_e64 v86, v195, v178, s[6:7]
	v_cndmask_b32_e64 v41, v198, v179, s[8:9]
	v_cndmask_b32_e64 v40, v192, v173, s[8:9]
	v_cndmask_b32_e64 v43, v200, v180, s[8:9]
	v_cndmask_b32_e64 v42, v194, v174, s[8:9]
	v_pk_fma_f32 v[86:87], v[8:9], v[86:87], v[12:13]
	v_pk_fma_f32 v[84:85], v[10:11], v[84:85], v[14:15]
	v_pk_fma_f32 v[40:41], v[0:1], v[40:41], v[86:87]
	v_pk_fma_f32 v[42:43], v[2:3], v[42:43], v[84:85]
	v_pk_fma_f32 v[82:83], v[4:5], v[82:83], v[40:41]
	v_pk_fma_f32 v[84:85], v[6:7], v[80:81], v[42:43]
	v_lshlrev_b32_e32 v40, 16, v170
	v_and_b32_e32 v41, 0xffff0000, v170
	v_lshlrev_b32_e32 v42, 16, v169
	v_and_b32_e32 v43, 0xffff0000, v169
	s_nop 1
	v_mov_b32_dpp v146, v40 row_ror:1 row_mask:0xf bank_mask:0xf
	v_mov_b32_dpp v169, v41 row_ror:1 row_mask:0xf bank_mask:0xf
	v_mov_b32_dpp v172, v40 row_ror:2 row_mask:0xf bank_mask:0xf
	v_mov_b32_dpp v175, v41 row_ror:2 row_mask:0xf bank_mask:0xf
	v_cndmask_b32_e64 v87, v89, v169, s[8:9]
	v_cndmask_b32_e64 v86, v88, v146, s[8:9]
	v_cndmask_b32_e64 v89, v93, v175, s[6:7]
	v_cndmask_b32_e64 v88, v92, v172, s[6:7]
	s_waitcnt vmcnt(2)
	v_pk_fma_f32 v[88:89], v[28:29], v[88:89], v[32:33]
	s_nop 1
	v_pk_fma_f32 v[86:87], v[20:21], v[86:87], v[88:89]
	s_nop 1
	v_pk_fma_f32 v[40:41], v[24:25], v[40:41], v[86:87]
	s_nop 1
	v_and_b32_e32 v89, 0x7fffffff, v41
	v_and_b32_e32 v88, 0x7fffffff, v40
	s_nop 1
	v_pk_fma_f32 v[88:89], v[88:89], s[52:53], 1.0 op_sel_hi:[1,0,0]
	v_mov_b32_dpp v170, v42 row_ror:1 row_mask:0xf bank_mask:0xf
	v_mov_b32_dpp v171, v43 row_ror:1 row_mask:0xf bank_mask:0xf
	v_mov_b32_dpp v192, v42 row_ror:2 row_mask:0xf bank_mask:0xf
	v_mov_b32_dpp v193, v43 row_ror:2 row_mask:0xf bank_mask:0xf
	v_rcp_f32_e32 v88, v88
	v_rcp_f32_e32 v89, v89
	v_cndmask_b32_e64 v81, v91, v171, s[8:9]
	v_cndmask_b32_e64 v80, v90, v170, s[8:9]
	v_cndmask_b32_e64 v91, v95, v193, s[6:7]
	v_cndmask_b32_e64 v90, v94, v192, s[6:7]
	v_pk_fma_f32 v[90:91], v[30:31], v[90:91], v[34:35]
	v_pk_mul_f32 v[86:87], v[40:41], v[40:41]
	v_pk_fma_f32 v[80:81], v[22:23], v[80:81], v[90:91]
	v_mov_b64_e32 v[90:91], s[56:57]
	v_pk_mul_f32 v[86:87], v[86:87], s[42:43] op_sel_hi:[1,0]
	v_pk_fma_f32 v[92:93], v[88:89], s[54:55], v[90:91] op_sel_hi:[1,0,0]
	v_exp_f32_e32 v86, v86
	v_exp_f32_e32 v87, v87
	v_pk_fma_f32 v[92:93], v[88:89], v[92:93], s[58:59] op_sel_hi:[1,1,0]
	v_cmp_gt_f32_e64 s[0:1], 0, v40
	v_pk_fma_f32 v[92:93], v[88:89], v[92:93], s[60:61] op_sel_hi:[1,1,0]
	v_pk_fma_f32 v[42:43], v[26:27], v[42:43], v[80:81]
	v_pk_fma_f32 v[92:93], v[88:89], v[92:93], s[62:63] op_sel_hi:[1,1,0]
	v_pk_mul_f32 v[80:81], v[42:43], v[42:43]
	v_pk_mul_f32 v[88:89], v[88:89], v[92:93]
	v_pk_mul_f32 v[80:81], v[80:81], s[42:43] op_sel_hi:[1,0]
	v_pk_mul_f32 v[86:87], v[86:87], v[88:89]
	v_exp_f32_e32 v80, v80
	v_pk_mul_f32 v[88:89], v[40:41], v[86:87]
	v_pk_fma_f32 v[86:87], v[40:41], v[86:87], v[40:41] neg_lo:[1,0,0] neg_hi:[1,0,0]
	v_exp_f32_e32 v81, v81
	v_cndmask_b32_e64 v40, v86, v88, s[0:1]
	v_cmp_gt_f32_e64 s[0:1], 0, v41
	v_and_b32_e32 v86, 0x7fffffff, v42
	v_add_u32_e32 v136, v45, v46
	v_cndmask_b32_e64 v41, v87, v89, s[0:1]
	v_and_b32_e32 v87, 0x7fffffff, v43
	v_pk_fma_f32 v[86:87], v[86:87], s[52:53], 1.0 op_sel_hi:[1,0,0]
	v_cmp_gt_f32_e64 s[0:1], 0, v42
	v_rcp_f32_e32 v86, v86
	v_rcp_f32_e32 v87, v87
	v_pk_mul_f32 v[36:37], v[36:37], v[40:41]
	s_nop 1
	v_cvt_pk_bf16_f32 v36, v36, v37
	v_pk_fma_f32 v[88:89], v[86:87], s[54:55], v[90:91] op_sel_hi:[1,0,0]
	s_nop 1
	v_pk_fma_f32 v[88:89], v[86:87], v[88:89], s[58:59] op_sel_hi:[1,1,0]
	s_nop 1
	v_pk_fma_f32 v[88:89], v[86:87], v[88:89], s[60:61] op_sel_hi:[1,1,0]
	s_nop 1
	v_pk_fma_f32 v[88:89], v[86:87], v[88:89], s[62:63] op_sel_hi:[1,1,0]
	s_nop 0
	v_pk_mul_f32 v[86:87], v[86:87], v[88:89]
	s_nop 0
	v_pk_mul_f32 v[80:81], v[80:81], v[86:87]
	s_nop 0
	v_pk_mul_f32 v[86:87], v[42:43], v[80:81]
	v_pk_fma_f32 v[80:81], v[42:43], v[80:81], v[42:43] neg_lo:[1,0,0] neg_hi:[1,0,0]
; __device__ __forceinline__ f32x4 gelu4(f32x4 v) { const f32x2 a = gelu_pk((f32x2){v[0], v[1]}), b = gelu_pk((f32x2){v[2], v[3]}); return (f32x4){a.x, a.y, b.x, b.y}; }
; __device__ __forceinline__ f32x4 ror1v(f32x4 v) { return (f32x4){dpp_ror1(v[0]), dpp_ror1(v[1]), dpp_ror1(v[2]), dpp_ror1(v[3])}; }
; __device__ __forceinline__ f32x4 ror2v(f32x4 v) { return (f32x4){dpp_ror2(v[0]), dpp_ror2(v[1]), dpp_ror2(v[2]), dpp_ror2(v[3])}; }
; __device__ __forceinline__ u32x2 pack4(f32x4 v) { return (u32x2){pk2(v[0], v[1]), pk2(v[2], v[3])}; }
;     __device__ __forceinline__ void operator()(AccRef acc, const Unit& u, int wr, int wc, int fr, int fq) const {
;     ...
;                         const f32x4 au = unpack4(pa[ai][1][m][n]);
;                         const f32x4 ru1 = ror1v(au), ru2 = ror2v(au);
;                         const f32x4 u1 = fr >= 1 ? ru1 : pu1, u2 = fr >= 2 ? ru2 : pu2;
;                         if (m == 0 && fr < 2) *(f32x4*)(edge + (unsigned)((grp * 4 + fr) * UPN + DFF + jn)) = au;
;                         if (m == 3 && fr >= 14) *(f32x4*)(edge + (unsigned)((grp * 4 + (fr - 12)) * UPN + DFF + jn)) = au;
;                         cu[m] = bu + wu0 * u2 + wu1 * u1 + wu2 * au;
;                         pu1 = ru1; pu2 = ru2; }
;                 }
;                 {
;                     const f32x4 wg0 = *(const f32x4*)(cw + jn), wg1 = *(const f32x4*)(cw + (UPN + jn)), wg2 = *(const f32x4*)(cw + (2 * UPN + jn)), bg = *(const f32x4*)(cb + jn);
;                     f32x4 pg1 = (f32x4){0.f, 0.f, 0.f, 0.f}, pg2 = pg1;
; #pragma unroll
;                     for (int m = 0; m < 4; ++m) { const int row = rowg + m * 16 + fr;
;                         const f32x4 ag = unpack4(pa[ai][0][m][n]);
;                         const f32x4 rg1 = ror1v(ag), rg2 = ror2v(ag);
;                         const f32x4 g1 = fr >= 1 ? rg1 : pg1, g2 = fr >= 2 ? rg2 : pg2;
;                         if (m == 0 && fr < 2) *(f32x4*)(edge + (unsigned)((grp * 4 + fr) * UPN + jn)) = ag;
;                         if (m == 3 && fr >= 14) *(f32x4*)(edge + (unsigned)((grp * 4 + (fr - 12)) * UPN + jn)) = ag;
;                         const f32x4 o = gelu4(bg + wg0 * g2 + wg1 * g1 + wg2 * ag) * cu[m];
;                         if (!(m == 0 && fr < 2)) *(u32x2*)(act + (unsigned)(row * DFF + jn)) = pack4(o);
;                         pg1 = rg1; pg2 = rg2; }
	s_nop 0
	v_cndmask_b32_e64 v42, v80, v86, s[0:1]
	v_cmp_gt_f32_e64 s[0:1], 0, v43
	s_nop 1
	s_nop 0
	v_cndmask_b32_e64 v43, v81, v87, s[0:1]
	v_pk_mul_f32 v[38:39], v[38:39], v[42:43]
	s_nop 1
	v_cvt_pk_bf16_f32 v37, v38, v39
	v_lshl_add_u64 v[38:39], v[136:137], 1, s[26:27]
	global_store_dwordx2 v[38:39], v[36:37], off
	v_lshlrev_b32_e32 v36, 16, v167
	v_and_b32_e32 v37, 0xffff0000, v167
	v_lshlrev_b32_e32 v38, 16, v168
	v_mov_b32_dpp v43, v36 row_ror:2 row_mask:0xf bank_mask:0xf
	v_mov_b32_dpp v80, v37 row_ror:2 row_mask:0xf bank_mask:0xf
	v_mov_b32_dpp v40, v36 row_ror:1 row_mask:0xf bank_mask:0xf
	v_mov_b32_dpp v41, v37 row_ror:1 row_mask:0xf bank_mask:0xf
	v_cndmask_b32_e64 v93, v175, v80, s[6:7]
	v_cndmask_b32_e64 v92, v172, v43, s[6:7]
	v_cndmask_b32_e64 v89, v169, v41, s[8:9]
	v_cndmask_b32_e64 v88, v146, v40, s[8:9]
	v_pk_fma_f32 v[92:93], v[28:29], v[92:93], v[32:33]
	v_and_b32_e32 v39, 0xffff0000, v168
	v_pk_fma_f32 v[88:89], v[20:21], v[88:89], v[92:93]
	s_nop 1
	v_pk_fma_f32 v[36:37], v[24:25], v[36:37], v[88:89]
	s_nop 1
	v_and_b32_e32 v93, 0x7fffffff, v37
	v_and_b32_e32 v92, 0x7fffffff, v36
	v_pk_fma_f32 v[92:93], v[92:93], s[52:53], 1.0 op_sel_hi:[1,0,0]
	v_mov_b32_dpp v45, v38 row_ror:2 row_mask:0xf bank_mask:0xf
	v_rcp_f32_e32 v92, v92
	v_rcp_f32_e32 v93, v93
	v_mov_b32_dpp v81, v39 row_ror:2 row_mask:0xf bank_mask:0xf
	v_mov_b32_dpp v42, v38 row_ror:1 row_mask:0xf bank_mask:0xf
	v_mov_b32_dpp v47, v39 row_ror:1 row_mask:0xf bank_mask:0xf
	v_cndmask_b32_e64 v95, v193, v81, s[6:7]
	v_cndmask_b32_e64 v94, v192, v45, s[6:7]
	v_cndmask_b32_e64 v87, v171, v47, s[8:9]
	v_cndmask_b32_e64 v86, v170, v42, s[8:9]
	v_pk_fma_f32 v[94:95], v[30:31], v[94:95], v[34:35]
	v_pk_mul_f32 v[88:89], v[36:37], v[36:37]
	v_pk_fma_f32 v[86:87], v[22:23], v[86:87], v[94:95]
	v_pk_mul_f32 v[88:89], v[88:89], s[42:43] op_sel_hi:[1,0]
	v_pk_fma_f32 v[94:95], v[92:93], s[54:55], v[90:91] op_sel_hi:[1,0,0]
	v_exp_f32_e32 v88, v88
	v_exp_f32_e32 v89, v89
	v_pk_fma_f32 v[94:95], v[92:93], v[94:95], s[58:59] op_sel_hi:[1,1,0]
	v_cmp_gt_f32_e64 s[0:1], 0, v36
	v_pk_fma_f32 v[94:95], v[92:93], v[94:95], s[60:61] op_sel_hi:[1,1,0]
	v_pk_fma_f32 v[38:39], v[26:27], v[38:39], v[86:87]
	v_pk_fma_f32 v[94:95], v[92:93], v[94:95], s[62:63] op_sel_hi:[1,1,0]
	v_pk_mul_f32 v[86:87], v[38:39], v[38:39]
	v_pk_mul_f32 v[92:93], v[92:93], v[94:95]
	v_pk_mul_f32 v[86:87], v[86:87], s[42:43] op_sel_hi:[1,0]
	v_pk_mul_f32 v[88:89], v[88:89], v[92:93]
	v_exp_f32_e32 v86, v86
	v_pk_mul_f32 v[92:93], v[36:37], v[88:89]
	v_pk_fma_f32 v[88:89], v[36:37], v[88:89], v[36:37] neg_lo:[1,0,0] neg_hi:[1,0,0]
	v_exp_f32_e32 v87, v87
	v_cndmask_b32_e64 v36, v88, v92, s[0:1]
	v_cmp_gt_f32_e64 s[0:1], 0, v37
	v_and_b32_e32 v88, 0x7fffffff, v38
	v_add_u32_e32 v136, v148, v46
	v_cndmask_b32_e64 v37, v89, v93, s[0:1]
	v_and_b32_e32 v89, 0x7fffffff, v39
	v_pk_fma_f32 v[88:89], v[88:89], s[52:53], 1.0 op_sel_hi:[1,0,0]
	v_cmp_gt_f32_e64 s[0:1], 0, v38
	v_rcp_f32_e32 v88, v88
	v_rcp_f32_e32 v89, v89
	v_pk_mul_f32 v[36:37], v[82:83], v[36:37]
	s_nop 1
	v_cvt_pk_bf16_f32 v36, v36, v37
	v_pk_fma_f32 v[90:91], v[88:89], s[54:55], v[90:91] op_sel_hi:[1,0,0]
	s_nop 1
	v_pk_fma_f32 v[90:91], v[88:89], v[90:91], s[58:59] op_sel_hi:[1,1,0]
	s_nop 0
	v_pk_fma_f32 v[90:91], v[88:89], v[90:91], s[60:61] op_sel_hi:[1,1,0]
	s_nop 0
	v_pk_fma_f32 v[90:91], v[88:89], v[90:91], s[62:63] op_sel_hi:[1,1,0]
	s_nop 0
	v_pk_mul_f32 v[88:89], v[88:89], v[90:91]
	s_nop 0
	v_pk_mul_f32 v[86:87], v[86:87], v[88:89]
	s_nop 0
	v_pk_mul_f32 v[88:89], v[38:39], v[86:87]
	v_pk_fma_f32 v[86:87], v[38:39], v[86:87], v[38:39] neg_lo:[1,0,0] neg_hi:[1,0,0]
	s_nop 0
	v_cndmask_b32_e64 v38, v86, v88, s[0:1]
	v_cmp_gt_f32_e64 s[0:1], 0, v39
	s_nop 1
	v_cndmask_b32_e64 v39, v87, v89, s[0:1]
	v_pk_mul_f32 v[38:39], v[84:85], v[38:39]
	s_nop 1
	v_cvt_pk_bf16_f32 v37, v38, v39
	v_lshl_add_u64 v[38:39], v[136:137], 1, s[26:27]
	global_store_dwordx2 v[38:39], v[36:37], off
	v_lshlrev_b32_e32 v36, 16, v147
	v_and_b32_e32 v37, 0xffff0000, v147
	v_lshlrev_b32_e32 v38, 16, v149
	v_and_b32_e32 v39, 0xffff0000, v149
	s_nop 1
	v_mov_b32_dpp v82, v36 row_ror:1 row_mask:0xf bank_mask:0xf
	v_mov_b32_dpp v83, v37 row_ror:1 row_mask:0xf bank_mask:0xf
	v_mov_b32_dpp v84, v38 row_ror:1 row_mask:0xf bank_mask:0xf
	v_mov_b32_dpp v87, v39 row_ror:1 row_mask:0xf bank_mask:0xf
	v_mov_b32_dpp v85, v36 row_ror:2 row_mask:0xf bank_mask:0xf
	v_mov_b32_dpp v88, v37 row_ror:2 row_mask:0xf bank_mask:0xf
	v_mov_b32_dpp v86, v38 row_ror:2 row_mask:0xf bank_mask:0xf
	v_mov_b32_dpp v89, v39 row_ror:2 row_mask:0xf bank_mask:0xf
	s_and_saveexec_b64 s[0:1], vcc
	s_cbranch_execz .LBB0_1426
	v_add_u32_e32 v136, v46, v152
	v_lshl_add_u64 v[90:91], v[136:137], 2, s[28:29]
	global_store_dwordx4 v[90:91], v[36:39], off

; __device__ __forceinline__ f32x4 gelu4(f32x4 v) { const f32x2 a = gelu_pk((f32x2){v[0], v[1]}), b = gelu_pk((f32x2){v[2], v[3]}); return (f32x4){a.x, a.y, b.x, b.y}; }
;     __device__ __forceinline__ void operator()(AccRef acc, const Unit& u, int wr, int wc, int fr, int fq) const {
;     ...
;                     const f32x4 wu0 = *(const f32x4*)(cw + (DFF + jn)), wu1 = *(const f32x4*)(cw + (UPN + DFF + jn)), wu2 = *(const f32x4*)(cw + (2 * UPN + DFF + jn)), bu = *(const f32x4*)(cb + (DFF + jn));
;                     f32x4 pu1 = (f32x4){0.f, 0.f, 0.f, 0.f}, pu2 = pu1;
; #pragma unroll
;                     for (int m = 0; m < 4; ++m) {
;                         const f32x4 au = unpack4(pa[ai][1][m][n]);
;                         const f32x4 ru1 = ror1v(au), ru2 = ror2v(au);
;                         const f32x4 u1 = fr >= 1 ? ru1 : pu1, u2 = fr >= 2 ? ru2 : pu2;
;                         if (m == 0 && fr < 2) *(f32x4*)(edge + (unsigned)((grp * 4 + fr) * UPN + DFF + jn)) = au;
;                         if (m == 3 && fr >= 14) *(f32x4*)(edge + (unsigned)((grp * 4 + (fr - 12)) * UPN + DFF + jn)) = au;
;                         cu[m] = bu + wu0 * u2 + wu1 * u1 + wu2 * au;
;                         pu1 = ru1; pu2 = ru2; }
;                 }
;                 {
;                     const f32x4 wg0 = *(const f32x4*)(cw + jn), wg1 = *(const f32x4*)(cw + (UPN + jn)), wg2 = *(const f32x4*)(cw + (2 * UPN + jn)), bg = *(const f32x4*)(cb + jn);
;                     f32x4 pg1 = (f32x4){0.f, 0.f, 0.f, 0.f}, pg2 = pg1;
; #pragma unroll
;                     for (int m = 0; m < 4; ++m) { const int row = rowg + m * 16 + fr;
;                         const f32x4 ag = unpack4(pa[ai][0][m][n]);
;                         const f32x4 rg1 = ror1v(ag), rg2 = ror2v(ag);
;                         const f32x4 g1 = fr >= 1 ? rg1 : pg1, g2 = fr >= 2 ? rg2 : pg2;
;                         if (m == 0 && fr < 2) *(f32x4*)(edge + (unsigned)((grp * 4 + fr) * UPN + jn)) = ag;
;                         if (m == 3 && fr >= 14) *(f32x4*)(edge + (unsigned)((grp * 4 + (fr - 12)) * UPN + jn)) = ag;
;                         const f32x4 o = gelu4(bg + wg0 * g2 + wg1 * g1 + wg2 * ag) * cu[m];
;                         if (!(m == 0 && fr < 2)) *(u32x2*)(act + (unsigned)(row * DFF + jn)) = pack4(o);
;                         pg1 = rg1; pg2 = rg2; }
.LBB0_1434:
	s_or_b64 exec, exec, s[0:1]
	s_nop 0
	v_cndmask_b32_e64 v41, v174, v175, s[6:7]
	v_cndmask_b32_e64 v40, v172, v173, s[6:7]
	v_cndmask_b32_e64 v43, v168, v171, s[6:7]
	v_cndmask_b32_e64 v42, v148, v152, s[6:7]
	v_cndmask_b32_e64 v37, v149, v169, s[8:9]
	v_cndmask_b32_e64 v36, v146, v123, s[8:9]
	v_cndmask_b32_e64 v39, v167, v170, s[8:9]
	v_cndmask_b32_e64 v38, v147, v150, s[8:9]
	s_waitcnt vmcnt(4)
	v_pk_fma_f32 v[42:43], v[8:9], v[42:43], v[12:13]
	v_pk_fma_f32 v[40:41], v[10:11], v[40:41], v[14:15]
	v_pk_fma_f32 v[36:37], v[4:5], v[36:37], v[42:43]
	v_pk_fma_f32 v[38:39], v[6:7], v[38:39], v[40:41]
	v_pk_fma_f32 v[36:37], v[0:1], v[54:55], v[36:37]
	v_pk_fma_f32 v[38:39], v[2:3], v[52:53], v[38:39]
	v_cndmask_b32_e64 v53, v175, v90, s[6:7]
	v_cndmask_b32_e64 v52, v173, v89, s[6:7]
	v_cndmask_b32_e64 v55, v171, v88, s[6:7]
	v_cndmask_b32_e64 v54, v152, v85, s[6:7]
	v_cndmask_b32_e64 v41, v169, v86, s[8:9]
	v_cndmask_b32_e64 v40, v123, v83, s[8:9]
	v_cndmask_b32_e64 v43, v170, v87, s[8:9]
	v_cndmask_b32_e64 v42, v150, v84, s[8:9]
	v_pk_fma_f32 v[54:55], v[8:9], v[54:55], v[12:13]
	v_pk_fma_f32 v[52:53], v[10:11], v[52:53], v[14:15]
	v_pk_fma_f32 v[40:41], v[4:5], v[40:41], v[54:55]
	v_pk_fma_f32 v[42:43], v[6:7], v[42:43], v[52:53]
	v_pk_fma_f32 v[52:53], v[0:1], v[50:51], v[40:41]
	v_pk_fma_f32 v[54:55], v[2:3], v[48:49], v[42:43]
	v_lshlrev_b32_e32 v40, 16, v116
	v_and_b32_e32 v41, 0xffff0000, v116
	v_lshlrev_b32_e32 v42, 16, v117
	v_and_b32_e32 v43, 0xffff0000, v117
	s_nop 1
	v_mov_b32_dpp v116, v40 row_ror:1 row_mask:0xf bank_mask:0xf
	v_mov_b32_dpp v117, v41 row_ror:1 row_mask:0xf bank_mask:0xf
	v_mov_b32_dpp v123, v40 row_ror:2 row_mask:0xf bank_mask:0xf
	v_mov_b32_dpp v124, v41 row_ror:2 row_mask:0xf bank_mask:0xf
	v_cndmask_b32_e64 v51, v57, v117, s[8:9]
	v_cndmask_b32_e64 v50, v56, v116, s[8:9]
	v_cndmask_b32_e64 v57, v63, v124, s[6:7]
	v_cndmask_b32_e64 v56, v62, v123, s[6:7]
	s_waitcnt vmcnt(2)
	v_pk_fma_f32 v[56:57], v[28:29], v[56:57], v[32:33]
	s_nop 1
	v_pk_fma_f32 v[50:51], v[24:25], v[50:51], v[56:57]
	s_nop 1
	v_pk_fma_f32 v[40:41], v[20:21], v[40:41], v[50:51]
	s_nop 1
	v_and_b32_e32 v57, 0x7fffffff, v41
	v_and_b32_e32 v56, 0x7fffffff, v40
	s_nop 1
	v_pk_fma_f32 v[56:57], v[56:57], s[52:53], 1.0 op_sel_hi:[1,0,0]
	v_mov_b32_dpp v118, v42 row_ror:1 row_mask:0xf bank_mask:0xf
	v_mov_b32_dpp v119, v43 row_ror:1 row_mask:0xf bank_mask:0xf
	v_mov_b32_dpp v125, v42 row_ror:2 row_mask:0xf bank_mask:0xf
	v_mov_b32_dpp v126, v43 row_ror:2 row_mask:0xf bank_mask:0xf
	v_rcp_f32_e32 v56, v56
	v_rcp_f32_e32 v57, v57
	v_cndmask_b32_e64 v49, v59, v119, s[8:9]
	v_cndmask_b32_e64 v48, v58, v118, s[8:9]
	v_cndmask_b32_e64 v59, v65, v126, s[6:7]
	v_cndmask_b32_e64 v58, v64, v125, s[6:7]
	v_pk_fma_f32 v[58:59], v[30:31], v[58:59], v[34:35]
	v_pk_mul_f32 v[50:51], v[40:41], v[40:41]
	v_pk_fma_f32 v[48:49], v[26:27], v[48:49], v[58:59]
	v_mov_b64_e32 v[58:59], s[56:57]
	v_pk_mul_f32 v[50:51], v[50:51], s[42:43] op_sel_hi:[1,0]
	v_pk_fma_f32 v[62:63], v[56:57], s[54:55], v[58:59] op_sel_hi:[1,0,0]
	v_exp_f32_e32 v50, v50
	v_exp_f32_e32 v51, v51
	v_pk_fma_f32 v[62:63], v[56:57], v[62:63], s[58:59] op_sel_hi:[1,1,0]
	v_cmp_gt_f32_e64 s[0:1], 0, v40
	v_pk_fma_f32 v[62:63], v[56:57], v[62:63], s[60:61] op_sel_hi:[1,1,0]
	v_pk_fma_f32 v[42:43], v[22:23], v[42:43], v[48:49]
	v_pk_fma_f32 v[62:63], v[56:57], v[62:63], s[62:63] op_sel_hi:[1,1,0]
	v_pk_mul_f32 v[48:49], v[42:43], v[42:43]
	v_pk_mul_f32 v[56:57], v[56:57], v[62:63]
	v_pk_mul_f32 v[48:49], v[48:49], s[42:43] op_sel_hi:[1,0]
	v_pk_mul_f32 v[50:51], v[50:51], v[56:57]
	v_exp_f32_e32 v48, v48
	v_pk_mul_f32 v[56:57], v[40:41], v[50:51]
	v_pk_fma_f32 v[50:51], v[40:41], v[50:51], v[40:41] neg_lo:[1,0,0] neg_hi:[1,0,0]
	v_exp_f32_e32 v49, v49
	v_cndmask_b32_e64 v40, v50, v56, s[0:1]
	v_cmp_gt_f32_e64 s[0:1], 0, v41
	v_and_b32_e32 v50, 0x7fffffff, v42
	v_add_u32_e32 v62, 0xb000, v82
	v_cndmask_b32_e64 v41, v51, v57, s[0:1]
	v_and_b32_e32 v51, 0x7fffffff, v43
	v_pk_fma_f32 v[50:51], v[50:51], s[52:53], 1.0 op_sel_hi:[1,0,0]
	v_cmp_gt_f32_e64 s[0:1], 0, v42
	v_rcp_f32_e32 v50, v50
	v_rcp_f32_e32 v51, v51
	v_pk_mul_f32 v[36:37], v[36:37], v[40:41]
	v_add_u32_e32 v136, v62, v44
	v_cvt_pk_bf16_f32 v36, v36, v37
	v_pk_fma_f32 v[56:57], v[50:51], s[54:55], v[58:59] op_sel_hi:[1,0,0]
	s_nop 1
	v_pk_fma_f32 v[56:57], v[50:51], v[56:57], s[58:59] op_sel_hi:[1,1,0]
	s_nop 1
	v_pk_fma_f32 v[56:57], v[50:51], v[56:57], s[60:61] op_sel_hi:[1,1,0]
	v_add_u32_e32 v63, 0x16000, v82
	v_pk_fma_f32 v[56:57], v[50:51], v[56:57], s[62:63] op_sel_hi:[1,1,0]
	s_nop 0
	v_pk_mul_f32 v[50:51], v[50:51], v[56:57]
	s_nop 0
	v_pk_mul_f32 v[48:49], v[48:49], v[50:51]
	s_nop 0
	v_pk_mul_f32 v[50:51], v[42:43], v[48:49]
	v_pk_fma_f32 v[48:49], v[42:43], v[48:49], v[42:43] neg_lo:[1,0,0] neg_hi:[1,0,0]
	s_nop 0
; __device__ __forceinline__ f32x4 gelu4(f32x4 v) { const f32x2 a = gelu_pk((f32x2){v[0], v[1]}), b = gelu_pk((f32x2){v[2], v[3]}); return (f32x4){a.x, a.y, b.x, b.y}; }
; __device__ __forceinline__ f32x4 ror1v(f32x4 v) { return (f32x4){dpp_ror1(v[0]), dpp_ror1(v[1]), dpp_ror1(v[2]), dpp_ror1(v[3])}; }
; __device__ __forceinline__ f32x4 ror2v(f32x4 v) { return (f32x4){dpp_ror2(v[0]), dpp_ror2(v[1]), dpp_ror2(v[2]), dpp_ror2(v[3])}; }
; __device__ __forceinline__ u32x2 pack4(f32x4 v) { return (u32x2){pk2(v[0], v[1]), pk2(v[2], v[3])}; }
;     __device__ __forceinline__ void operator()(AccRef acc, const Unit& u, int wr, int wc, int fr, int fq) const {
;     ...
;                         const f32x4 au = unpack4(pa[ai][1][m][n]);
;                         const f32x4 ru1 = ror1v(au), ru2 = ror2v(au);
;                         const f32x4 u1 = fr >= 1 ? ru1 : pu1, u2 = fr >= 2 ? ru2 : pu2;
;                         if (m == 0 && fr < 2) *(f32x4*)(edge + (unsigned)((grp * 4 + fr) * UPN + DFF + jn)) = au;
;                         if (m == 3 && fr >= 14) *(f32x4*)(edge + (unsigned)((grp * 4 + (fr - 12)) * UPN + DFF + jn)) = au;
;                         cu[m] = bu + wu0 * u2 + wu1 * u1 + wu2 * au;
;                         pu1 = ru1; pu2 = ru2; }
;                 }
;                 {
;                     const f32x4 wg0 = *(const f32x4*)(cw + jn), wg1 = *(const f32x4*)(cw + (UPN + jn)), wg2 = *(const f32x4*)(cw + (2 * UPN + jn)), bg = *(const f32x4*)(cb + jn);
;                     f32x4 pg1 = (f32x4){0.f, 0.f, 0.f, 0.f}, pg2 = pg1;
; #pragma unroll
;                     for (int m = 0; m < 4; ++m) { const int row = rowg + m * 16 + fr;
;                         const f32x4 ag = unpack4(pa[ai][0][m][n]);
;                         const f32x4 rg1 = ror1v(ag), rg2 = ror2v(ag);
;                         const f32x4 g1 = fr >= 1 ? rg1 : pg1, g2 = fr >= 2 ? rg2 : pg2;
;                         if (m == 0 && fr < 2) *(f32x4*)(edge + (unsigned)((grp * 4 + fr) * UPN + jn)) = ag;
;                         if (m == 3 && fr >= 14) *(f32x4*)(edge + (unsigned)((grp * 4 + (fr - 12)) * UPN + jn)) = ag;
;                         const f32x4 o = gelu4(bg + wg0 * g2 + wg1 * g1 + wg2 * ag) * cu[m];
;                         if (!(m == 0 && fr < 2)) *(u32x2*)(act + (unsigned)(row * DFF + jn)) = pack4(o);
;                         pg1 = rg1; pg2 = rg2; }
	v_cndmask_b32_e64 v42, v48, v50, s[0:1]
	v_cmp_gt_f32_e64 s[0:1], 0, v43
	s_nop 1
	v_cndmask_b32_e64 v43, v49, v51, s[0:1]
	v_pk_mul_f32 v[38:39], v[38:39], v[42:43]
	s_nop 1
	v_cvt_pk_bf16_f32 v37, v38, v39
	v_lshl_add_u64 v[38:39], v[136:137], 1, s[26:27]
	global_store_dwordx2 v[38:39], v[36:37], off
	v_lshlrev_b32_e32 v36, 16, v114
	v_and_b32_e32 v37, 0xffff0000, v114
	v_lshlrev_b32_e32 v38, 16, v115
	v_mov_b32_dpp v43, v36 row_ror:2 row_mask:0xf bank_mask:0xf
	v_mov_b32_dpp v50, v37 row_ror:2 row_mask:0xf bank_mask:0xf
	v_and_b32_e32 v39, 0xffff0000, v115
	v_mov_b32_dpp v40, v36 row_ror:1 row_mask:0xf bank_mask:0xf
	v_mov_b32_dpp v41, v37 row_ror:1 row_mask:0xf bank_mask:0xf
	v_cndmask_b32_e64 v115, v124, v50, s[6:7]
	v_cndmask_b32_e64 v114, v123, v43, s[6:7]
	v_cndmask_b32_e64 v65, v117, v41, s[8:9]
	v_cndmask_b32_e64 v64, v116, v40, s[8:9]
	v_pk_fma_f32 v[114:115], v[28:29], v[114:115], v[32:33]
	s_nop 1
	v_pk_fma_f32 v[64:65], v[24:25], v[64:65], v[114:115]
	s_nop 1
	v_pk_fma_f32 v[36:37], v[20:21], v[36:37], v[64:65]
	s_nop 1
	v_and_b32_e32 v115, 0x7fffffff, v37
	v_and_b32_e32 v114, 0x7fffffff, v36
	v_pk_fma_f32 v[114:115], v[114:115], s[52:53], 1.0 op_sel_hi:[1,0,0]
	v_mov_b32_dpp v48, v38 row_ror:2 row_mask:0xf bank_mask:0xf
	v_rcp_f32_e32 v114, v114
	v_rcp_f32_e32 v115, v115
	v_mov_b32_dpp v51, v39 row_ror:2 row_mask:0xf bank_mask:0xf
	v_mov_b32_dpp v42, v38 row_ror:1 row_mask:0xf bank_mask:0xf
	v_mov_b32_dpp v49, v39 row_ror:1 row_mask:0xf bank_mask:0xf
	v_cndmask_b32_e64 v117, v126, v51, s[6:7]
	v_cndmask_b32_e64 v116, v125, v48, s[6:7]
	v_cndmask_b32_e64 v57, v119, v49, s[8:9]
	v_cndmask_b32_e64 v56, v118, v42, s[8:9]
	v_pk_fma_f32 v[116:117], v[30:31], v[116:117], v[34:35]
	v_pk_mul_f32 v[64:65], v[36:37], v[36:37]
	v_pk_fma_f32 v[56:57], v[26:27], v[56:57], v[116:117]
	v_pk_mul_f32 v[64:65], v[64:65], s[42:43] op_sel_hi:[1,0]
	v_pk_fma_f32 v[116:117], v[114:115], s[54:55], v[58:59] op_sel_hi:[1,0,0]
	v_exp_f32_e32 v64, v64
	v_exp_f32_e32 v65, v65
	v_pk_fma_f32 v[116:117], v[114:115], v[116:117], s[58:59] op_sel_hi:[1,1,0]
	v_cmp_gt_f32_e64 s[0:1], 0, v36
	v_pk_fma_f32 v[116:117], v[114:115], v[116:117], s[60:61] op_sel_hi:[1,1,0]
	v_pk_fma_f32 v[38:39], v[22:23], v[38:39], v[56:57]
	v_pk_fma_f32 v[116:117], v[114:115], v[116:117], s[62:63] op_sel_hi:[1,1,0]
	v_pk_mul_f32 v[56:57], v[38:39], v[38:39]
	v_pk_mul_f32 v[114:115], v[114:115], v[116:117]
	v_pk_mul_f32 v[56:57], v[56:57], s[42:43] op_sel_hi:[1,0]
	v_pk_mul_f32 v[64:65], v[64:65], v[114:115]
	v_exp_f32_e32 v56, v56
	v_pk_mul_f32 v[114:115], v[36:37], v[64:65]
	v_pk_fma_f32 v[64:65], v[36:37], v[64:65], v[36:37] neg_lo:[1,0,0] neg_hi:[1,0,0]
	v_exp_f32_e32 v57, v57
	v_cndmask_b32_e64 v36, v64, v114, s[0:1]
	v_cmp_gt_f32_e64 s[0:1], 0, v37
	v_and_b32_e32 v64, 0x7fffffff, v38
	v_add_u32_e32 v136, v63, v44
	v_cndmask_b32_e64 v37, v65, v115, s[0:1]
	v_and_b32_e32 v65, 0x7fffffff, v39
	v_pk_fma_f32 v[64:65], v[64:65], s[52:53], 1.0 op_sel_hi:[1,0,0]
	v_cmp_gt_f32_e64 s[0:1], 0, v38
	v_rcp_f32_e32 v64, v64
	v_rcp_f32_e32 v65, v65
	v_pk_mul_f32 v[36:37], v[52:53], v[36:37]
	s_nop 1
	v_cvt_pk_bf16_f32 v36, v36, v37
	v_pk_fma_f32 v[58:59], v[64:65], s[54:55], v[58:59] op_sel_hi:[1,0,0]
	s_nop 1
	v_pk_fma_f32 v[58:59], v[64:65], v[58:59], s[58:59] op_sel_hi:[1,1,0]
	s_nop 0
	v_pk_fma_f32 v[58:59], v[64:65], v[58:59], s[60:61] op_sel_hi:[1,1,0]
	s_nop 0
	v_pk_fma_f32 v[58:59], v[64:65], v[58:59], s[62:63] op_sel_hi:[1,1,0]
	s_nop 0
	v_pk_mul_f32 v[58:59], v[64:65], v[58:59]
	s_nop 0
	v_pk_mul_f32 v[56:57], v[56:57], v[58:59]
	s_nop 0
	v_pk_mul_f32 v[58:59], v[38:39], v[56:57]
	v_pk_fma_f32 v[56:57], v[38:39], v[56:57], v[38:39] neg_lo:[1,0,0] neg_hi:[1,0,0]
	s_nop 0
	v_cndmask_b32_e64 v38, v56, v58, s[0:1]
	v_cmp_gt_f32_e64 s[0:1], 0, v39
	s_nop 1
	v_cndmask_b32_e64 v39, v57, v59, s[0:1]
	v_pk_mul_f32 v[38:39], v[54:55], v[38:39]
	s_nop 1
	v_cvt_pk_bf16_f32 v37, v38, v39
	v_lshl_add_u64 v[38:39], v[136:137], 1, s[26:27]
	global_store_dwordx2 v[38:39], v[36:37], off
	v_lshlrev_b32_e32 v36, 16, v112
	v_and_b32_e32 v37, 0xffff0000, v112
	v_lshlrev_b32_e32 v38, 16, v113
	v_and_b32_e32 v39, 0xffff0000, v113
	s_nop 1
	v_mov_b32_dpp v52, v36 row_ror:1 row_mask:0xf bank_mask:0xf
	v_mov_b32_dpp v53, v37 row_ror:1 row_mask:0xf bank_mask:0xf
	v_mov_b32_dpp v54, v38 row_ror:1 row_mask:0xf bank_mask:0xf
	v_mov_b32_dpp v57, v39 row_ror:1 row_mask:0xf bank_mask:0xf
	v_mov_b32_dpp v55, v36 row_ror:2 row_mask:0xf bank_mask:0xf
	v_mov_b32_dpp v58, v37 row_ror:2 row_mask:0xf bank_mask:0xf
	v_mov_b32_dpp v56, v38 row_ror:2 row_mask:0xf bank_mask:0xf
	v_mov_b32_dpp v59, v39 row_ror:2 row_mask:0xf bank_mask:0xf
	s_and_saveexec_b64 s[0:1], vcc
	s_cbranch_execz .LBB0_1436
	v_add_u32_e32 v136, v47, v44
	v_lshl_add_u64 v[64:65], v[136:137], 2, s[28:29]
	global_store_dwordx4 v[64:65], v[36:39], off

; __device__ __forceinline__ f32x4 gelu4(f32x4 v) { const f32x2 a = gelu_pk((f32x2){v[0], v[1]}), b = gelu_pk((f32x2){v[2], v[3]}); return (f32x4){a.x, a.y, b.x, b.y}; }
;     __device__ __forceinline__ void operator()(AccRef acc, const Unit& u, int wr, int wc, int fr, int fq) const {
;     ...
;                     const f32x4 wu0 = *(const f32x4*)(cw + (DFF + jn)), wu1 = *(const f32x4*)(cw + (UPN + DFF + jn)), wu2 = *(const f32x4*)(cw + (2 * UPN + DFF + jn)), bu = *(const f32x4*)(cb + (DFF + jn));
;                     f32x4 pu1 = (f32x4){0.f, 0.f, 0.f, 0.f}, pu2 = pu1;
; #pragma unroll
;                     for (int m = 0; m < 4; ++m) {
;                         const f32x4 au = unpack4(pa[ai][1][m][n]);
;                         const f32x4 ru1 = ror1v(au), ru2 = ror2v(au);
;                         const f32x4 u1 = fr >= 1 ? ru1 : pu1, u2 = fr >= 2 ? ru2 : pu2;
;                         if (m == 0 && fr < 2) *(f32x4*)(edge + (unsigned)((grp * 4 + fr) * UPN + DFF + jn)) = au;
;                         if (m == 3 && fr >= 14) *(f32x4*)(edge + (unsigned)((grp * 4 + (fr - 12)) * UPN + DFF + jn)) = au;
;                         cu[m] = bu + wu0 * u2 + wu1 * u1 + wu2 * au;
;                         pu1 = ru1; pu2 = ru2; }
;                 }
;                 {
;                     const f32x4 wg0 = *(const f32x4*)(cw + jn), wg1 = *(const f32x4*)(cw + (UPN + jn)), wg2 = *(const f32x4*)(cw + (2 * UPN + jn)), bg = *(const f32x4*)(cb + jn);
;                     f32x4 pg1 = (f32x4){0.f, 0.f, 0.f, 0.f}, pg2 = pg1;
; #pragma unroll
;                     for (int m = 0; m < 4; ++m) { const int row = rowg + m * 16 + fr;
;                         const f32x4 ag = unpack4(pa[ai][0][m][n]);
;                         const f32x4 rg1 = ror1v(ag), rg2 = ror2v(ag);
;                         const f32x4 g1 = fr >= 1 ? rg1 : pg1, g2 = fr >= 2 ? rg2 : pg2;
;                         if (m == 0 && fr < 2) *(f32x4*)(edge + (unsigned)((grp * 4 + fr) * UPN + jn)) = ag;
;                         if (m == 3 && fr >= 14) *(f32x4*)(edge + (unsigned)((grp * 4 + (fr - 12)) * UPN + jn)) = ag;
;                         const f32x4 o = gelu4(bg + wg0 * g2 + wg1 * g1 + wg2 * ag) * cu[m];
;                         if (!(m == 0 && fr < 2)) *(u32x2*)(act + (unsigned)(row * DFF + jn)) = pack4(o);
;                         pg1 = rg1; pg2 = rg2; }
.LBB0_1444:
	s_or_b64 exec, exec, s[0:1]
	s_nop 0
	v_cndmask_b32_e64 v43, v115, v113, s[6:7]
	v_cndmask_b32_e64 v42, v105, v95, s[6:7]
	v_cndmask_b32_e64 v37, v112, v106, s[8:9]
	v_cndmask_b32_e64 v36, v93, v92, s[8:9]
	v_cndmask_b32_e64 v41, v119, v118, s[6:7]
	v_cndmask_b32_e64 v40, v117, v116, s[6:7]
	s_waitcnt vmcnt(4)
	v_pk_fma_f32 v[42:43], v[8:9], v[42:43], v[12:13]
	v_cndmask_b32_e64 v39, v114, v107, s[8:9]
	v_cndmask_b32_e64 v38, v104, v94, s[8:9]
	v_pk_fma_f32 v[40:41], v[10:11], v[40:41], v[14:15]
	v_pk_fma_f32 v[36:37], v[4:5], v[36:37], v[42:43]
	v_pk_fma_f32 v[38:39], v[6:7], v[38:39], v[40:41]
	v_pk_fma_f32 v[36:37], v[0:1], v[52:53], v[36:37]
	v_cndmask_b32_e64 v53, v113, v70, s[6:7]
	v_cndmask_b32_e64 v52, v95, v67, s[6:7]
	v_pk_fma_f32 v[38:39], v[2:3], v[50:51], v[38:39]
	v_cndmask_b32_e64 v41, v106, v68, s[8:9]
	v_cndmask_b32_e64 v40, v92, v65, s[8:9]
	v_cndmask_b32_e64 v51, v118, v83, s[6:7]
	v_cndmask_b32_e64 v50, v116, v71, s[6:7]
	v_pk_fma_f32 v[52:53], v[8:9], v[52:53], v[12:13]
	v_cndmask_b32_e64 v43, v107, v69, s[8:9]
	v_cndmask_b32_e64 v42, v94, v66, s[8:9]
	v_pk_fma_f32 v[50:51], v[10:11], v[50:51], v[14:15]
	v_pk_fma_f32 v[40:41], v[4:5], v[40:41], v[52:53]
	v_pk_fma_f32 v[42:43], v[6:7], v[42:43], v[50:51]
	v_pk_fma_f32 v[50:51], v[0:1], v[48:49], v[40:41]
	v_lshlrev_b32_e32 v40, 16, v100
	v_and_b32_e32 v41, 0xffff0000, v100
	s_nop 1
	v_mov_b32_dpp v72, v40 row_ror:1 row_mask:0xf bank_mask:0xf
	v_mov_b32_dpp v73, v41 row_ror:1 row_mask:0xf bank_mask:0xf
	v_mov_b32_dpp v76, v40 row_ror:2 row_mask:0xf bank_mask:0xf
	v_mov_b32_dpp v77, v41 row_ror:2 row_mask:0xf bank_mask:0xf
	v_cndmask_b32_e64 v49, v55, v73, s[8:9]
	v_cndmask_b32_e64 v48, v54, v72, s[8:9]
	v_cndmask_b32_e64 v55, v59, v77, s[6:7]
	v_cndmask_b32_e64 v54, v58, v76, s[6:7]
	s_waitcnt vmcnt(2)
	v_pk_fma_f32 v[54:55], v[28:29], v[54:55], v[32:33]
	v_pk_fma_f32 v[52:53], v[2:3], v[44:45], v[42:43]
	v_pk_fma_f32 v[48:49], v[24:25], v[48:49], v[54:55]
	v_lshlrev_b32_e32 v42, 16, v101
	v_pk_fma_f32 v[40:41], v[20:21], v[40:41], v[48:49]
	v_and_b32_e32 v43, 0xffff0000, v101
	v_and_b32_e32 v55, 0x7fffffff, v41
	v_and_b32_e32 v54, 0x7fffffff, v40
	s_nop 1
	v_pk_fma_f32 v[54:55], v[54:55], s[52:53], 1.0 op_sel_hi:[1,0,0]
	v_mov_b32_dpp v74, v42 row_ror:1 row_mask:0xf bank_mask:0xf
	v_mov_b32_dpp v75, v43 row_ror:1 row_mask:0xf bank_mask:0xf
	v_mov_b32_dpp v78, v42 row_ror:2 row_mask:0xf bank_mask:0xf
	v_mov_b32_dpp v79, v43 row_ror:2 row_mask:0xf bank_mask:0xf
	v_rcp_f32_e32 v54, v54
	v_rcp_f32_e32 v55, v55
	v_cndmask_b32_e64 v45, v57, v75, s[8:9]
	v_cndmask_b32_e64 v44, v56, v74, s[8:9]
	v_cndmask_b32_e64 v57, v61, v79, s[6:7]
	v_cndmask_b32_e64 v56, v60, v78, s[6:7]
	v_pk_fma_f32 v[56:57], v[30:31], v[56:57], v[34:35]
	v_pk_mul_f32 v[48:49], v[40:41], v[40:41]
	v_pk_fma_f32 v[44:45], v[26:27], v[44:45], v[56:57]
	v_mov_b64_e32 v[56:57], s[56:57]
	v_pk_mul_f32 v[48:49], v[48:49], s[42:43] op_sel_hi:[1,0]
	v_pk_fma_f32 v[58:59], v[54:55], s[54:55], v[56:57] op_sel_hi:[1,0,0]
	v_exp_f32_e32 v48, v48
	v_exp_f32_e32 v49, v49
	v_pk_fma_f32 v[58:59], v[54:55], v[58:59], s[58:59] op_sel_hi:[1,1,0]
	v_cmp_gt_f32_e64 s[0:1], 0, v40
	v_pk_fma_f32 v[58:59], v[54:55], v[58:59], s[60:61] op_sel_hi:[1,1,0]
	v_pk_fma_f32 v[42:43], v[22:23], v[42:43], v[44:45]
	v_pk_fma_f32 v[58:59], v[54:55], v[58:59], s[62:63] op_sel_hi:[1,1,0]
	v_pk_mul_f32 v[44:45], v[42:43], v[42:43]
	v_pk_mul_f32 v[54:55], v[54:55], v[58:59]
	v_pk_mul_f32 v[44:45], v[44:45], s[42:43] op_sel_hi:[1,0]
	v_pk_mul_f32 v[48:49], v[48:49], v[54:55]
	v_exp_f32_e32 v44, v44
	v_pk_mul_f32 v[54:55], v[40:41], v[48:49]
	v_pk_fma_f32 v[48:49], v[40:41], v[48:49], v[40:41] neg_lo:[1,0,0] neg_hi:[1,0,0]
	v_exp_f32_e32 v45, v45
	v_cndmask_b32_e64 v40, v48, v54, s[0:1]
	v_cmp_gt_f32_e64 s[0:1], 0, v41
	v_and_b32_e32 v48, 0x7fffffff, v42
	v_add_u32_e32 v136, v62, v46
	v_cndmask_b32_e64 v41, v49, v55, s[0:1]
	v_and_b32_e32 v49, 0x7fffffff, v43
	v_pk_fma_f32 v[48:49], v[48:49], s[52:53], 1.0 op_sel_hi:[1,0,0]
	v_cmp_gt_f32_e64 s[0:1], 0, v42
	v_rcp_f32_e32 v48, v48
	v_rcp_f32_e32 v49, v49
	v_pk_mul_f32 v[36:37], v[36:37], v[40:41]
	s_nop 1
	v_cvt_pk_bf16_f32 v36, v36, v37
	v_pk_fma_f32 v[54:55], v[48:49], s[54:55], v[56:57] op_sel_hi:[1,0,0]
	s_nop 1
	v_pk_fma_f32 v[54:55], v[48:49], v[54:55], s[58:59] op_sel_hi:[1,1,0]
	s_nop 0
	v_pk_fma_f32 v[54:55], v[48:49], v[54:55], s[60:61] op_sel_hi:[1,1,0]
	s_nop 0
	v_pk_fma_f32 v[54:55], v[48:49], v[54:55], s[62:63] op_sel_hi:[1,1,0]
	s_nop 0
	v_pk_mul_f32 v[48:49], v[48:49], v[54:55]
	s_nop 0
	v_pk_mul_f32 v[44:45], v[44:45], v[48:49]
	s_nop 0
	v_pk_mul_f32 v[48:49], v[42:43], v[44:45]
	v_pk_fma_f32 v[44:45], v[42:43], v[44:45], v[42:43] neg_lo:[1,0,0] neg_hi:[1,0,0]
	s_nop 0
; __device__ __forceinline__ f32x4 gelu4(f32x4 v) { const f32x2 a = gelu_pk((f32x2){v[0], v[1]}), b = gelu_pk((f32x2){v[2], v[3]}); return (f32x4){a.x, a.y, b.x, b.y}; }
; __device__ __forceinline__ f32x4 ror1v(f32x4 v) { return (f32x4){dpp_ror1(v[0]), dpp_ror1(v[1]), dpp_ror1(v[2]), dpp_ror1(v[3])}; }
; __device__ __forceinline__ f32x4 ror2v(f32x4 v) { return (f32x4){dpp_ror2(v[0]), dpp_ror2(v[1]), dpp_ror2(v[2]), dpp_ror2(v[3])}; }
; __device__ __forceinline__ u32x2 pack4(f32x4 v) { return (u32x2){pk2(v[0], v[1]), pk2(v[2], v[3])}; }
;     __device__ __forceinline__ void operator()(AccRef acc, const Unit& u, int wr, int wc, int fr, int fq) const {
;     ...
;                         const f32x4 au = unpack4(pa[ai][1][m][n]);
;                         const f32x4 ru1 = ror1v(au), ru2 = ror2v(au);
;                         const f32x4 u1 = fr >= 1 ? ru1 : pu1, u2 = fr >= 2 ? ru2 : pu2;
;                         if (m == 0 && fr < 2) *(f32x4*)(edge + (unsigned)((grp * 4 + fr) * UPN + DFF + jn)) = au;
;                         if (m == 3 && fr >= 14) *(f32x4*)(edge + (unsigned)((grp * 4 + (fr - 12)) * UPN + DFF + jn)) = au;
;                         cu[m] = bu + wu0 * u2 + wu1 * u1 + wu2 * au;
;                         pu1 = ru1; pu2 = ru2; }
;                 }
;                 {
;                     const f32x4 wg0 = *(const f32x4*)(cw + jn), wg1 = *(const f32x4*)(cw + (UPN + jn)), wg2 = *(const f32x4*)(cw + (2 * UPN + jn)), bg = *(const f32x4*)(cb + jn);
;                     f32x4 pg1 = (f32x4){0.f, 0.f, 0.f, 0.f}, pg2 = pg1;
; #pragma unroll
;                     for (int m = 0; m < 4; ++m) { const int row = rowg + m * 16 + fr;
;                         const f32x4 ag = unpack4(pa[ai][0][m][n]);
;                         const f32x4 rg1 = ror1v(ag), rg2 = ror2v(ag);
;                         const f32x4 g1 = fr >= 1 ? rg1 : pg1, g2 = fr >= 2 ? rg2 : pg2;
;                         if (m == 0 && fr < 2) *(f32x4*)(edge + (unsigned)((grp * 4 + fr) * UPN + jn)) = ag;
;                         if (m == 3 && fr >= 14) *(f32x4*)(edge + (unsigned)((grp * 4 + (fr - 12)) * UPN + jn)) = ag;
;                         const f32x4 o = gelu4(bg + wg0 * g2 + wg1 * g1 + wg2 * ag) * cu[m];
;                         if (!(m == 0 && fr < 2)) *(u32x2*)(act + (unsigned)(row * DFF + jn)) = pack4(o);
;                         pg1 = rg1; pg2 = rg2; }
	v_cndmask_b32_e64 v42, v44, v48, s[0:1]
	v_cmp_gt_f32_e64 s[0:1], 0, v43
	s_nop 1
	v_cndmask_b32_e64 v43, v45, v49, s[0:1]
	v_pk_mul_f32 v[38:39], v[38:39], v[42:43]
	s_nop 1
	v_cvt_pk_bf16_f32 v37, v38, v39
	v_lshl_add_u64 v[38:39], v[136:137], 1, s[26:27]
	global_store_dwordx2 v[38:39], v[36:37], off
	v_lshlrev_b32_e32 v36, 16, v98
	v_and_b32_e32 v37, 0xffff0000, v98
	v_lshlrev_b32_e32 v38, 16, v99
	v_mov_b32_dpp v44, v36 row_ror:2 row_mask:0xf bank_mask:0xf
	v_mov_b32_dpp v48, v37 row_ror:2 row_mask:0xf bank_mask:0xf
	v_mov_b32_dpp v40, v36 row_ror:1 row_mask:0xf bank_mask:0xf
	v_mov_b32_dpp v41, v37 row_ror:1 row_mask:0xf bank_mask:0xf
	v_cndmask_b32_e64 v61, v77, v48, s[6:7]
	v_cndmask_b32_e64 v60, v76, v44, s[6:7]
	v_cndmask_b32_e64 v59, v73, v41, s[8:9]
	v_cndmask_b32_e64 v58, v72, v40, s[8:9]
	v_pk_fma_f32 v[60:61], v[28:29], v[60:61], v[32:33]
	v_and_b32_e32 v39, 0xffff0000, v99
	v_pk_fma_f32 v[58:59], v[24:25], v[58:59], v[60:61]
	s_nop 1
	v_pk_fma_f32 v[36:37], v[20:21], v[36:37], v[58:59]
	s_nop 1
	v_and_b32_e32 v61, 0x7fffffff, v37
	v_and_b32_e32 v60, 0x7fffffff, v36
	v_pk_fma_f32 v[60:61], v[60:61], s[52:53], 1.0 op_sel_hi:[1,0,0]
	s_nop 1
	v_rcp_f32_e32 v60, v60
	v_rcp_f32_e32 v61, v61
	v_mov_b32_dpp v45, v38 row_ror:2 row_mask:0xf bank_mask:0xf
	v_mov_b32_dpp v49, v39 row_ror:2 row_mask:0xf bank_mask:0xf
	v_mov_b32_dpp v42, v38 row_ror:1 row_mask:0xf bank_mask:0xf
	v_mov_b32_dpp v43, v39 row_ror:1 row_mask:0xf bank_mask:0xf
	v_cndmask_b32_e64 v73, v79, v49, s[6:7]
	v_cndmask_b32_e64 v72, v78, v45, s[6:7]
	v_cndmask_b32_e64 v55, v75, v43, s[8:9]
	v_cndmask_b32_e64 v54, v74, v42, s[8:9]
	v_pk_fma_f32 v[72:73], v[30:31], v[72:73], v[34:35]
	v_pk_mul_f32 v[58:59], v[36:37], v[36:37]
	v_pk_fma_f32 v[54:55], v[26:27], v[54:55], v[72:73]
	v_pk_mul_f32 v[58:59], v[58:59], s[42:43] op_sel_hi:[1,0]
	v_pk_fma_f32 v[72:73], v[60:61], s[54:55], v[56:57] op_sel_hi:[1,0,0]
	v_exp_f32_e32 v58, v58
	v_exp_f32_e32 v59, v59
	v_pk_fma_f32 v[72:73], v[60:61], v[72:73], s[58:59] op_sel_hi:[1,1,0]
	v_cmp_gt_f32_e64 s[0:1], 0, v36
	v_pk_fma_f32 v[72:73], v[60:61], v[72:73], s[60:61] op_sel_hi:[1,1,0]
	v_pk_fma_f32 v[38:39], v[22:23], v[38:39], v[54:55]
	v_pk_fma_f32 v[72:73], v[60:61], v[72:73], s[62:63] op_sel_hi:[1,1,0]
	v_pk_mul_f32 v[54:55], v[38:39], v[38:39]
	v_pk_mul_f32 v[60:61], v[60:61], v[72:73]
	v_pk_mul_f32 v[54:55], v[54:55], s[42:43] op_sel_hi:[1,0]
	v_pk_mul_f32 v[58:59], v[58:59], v[60:61]
	v_exp_f32_e32 v54, v54
	v_pk_mul_f32 v[60:61], v[36:37], v[58:59]
	v_pk_fma_f32 v[58:59], v[36:37], v[58:59], v[36:37] neg_lo:[1,0,0] neg_hi:[1,0,0]
	v_exp_f32_e32 v55, v55
	v_cndmask_b32_e64 v36, v58, v60, s[0:1]
	v_cmp_gt_f32_e64 s[0:1], 0, v37
	v_and_b32_e32 v58, 0x7fffffff, v38
	v_add_u32_e32 v136, v63, v46
	v_cndmask_b32_e64 v37, v59, v61, s[0:1]
	v_and_b32_e32 v59, 0x7fffffff, v39
	v_pk_fma_f32 v[58:59], v[58:59], s[52:53], 1.0 op_sel_hi:[1,0,0]
	v_cmp_gt_f32_e64 s[0:1], 0, v38
	v_rcp_f32_e32 v58, v58
	v_rcp_f32_e32 v59, v59
	v_pk_mul_f32 v[36:37], v[50:51], v[36:37]
	s_nop 1
	v_cvt_pk_bf16_f32 v36, v36, v37
	v_pk_fma_f32 v[56:57], v[58:59], s[54:55], v[56:57] op_sel_hi:[1,0,0]
	s_nop 1
	v_pk_fma_f32 v[56:57], v[58:59], v[56:57], s[58:59] op_sel_hi:[1,1,0]
	s_nop 0
	v_pk_fma_f32 v[56:57], v[58:59], v[56:57], s[60:61] op_sel_hi:[1,1,0]
	s_nop 0
	v_pk_fma_f32 v[56:57], v[58:59], v[56:57], s[62:63] op_sel_hi:[1,1,0]
	s_nop 0
	v_pk_mul_f32 v[56:57], v[58:59], v[56:57]
	s_nop 0
	v_pk_mul_f32 v[54:55], v[54:55], v[56:57]
	s_nop 0
	v_pk_mul_f32 v[56:57], v[38:39], v[54:55]
	v_pk_fma_f32 v[54:55], v[38:39], v[54:55], v[38:39] neg_lo:[1,0,0] neg_hi:[1,0,0]
	s_nop 0
	v_cndmask_b32_e64 v38, v54, v56, s[0:1]
	v_cmp_gt_f32_e64 s[0:1], 0, v39
	s_nop 1
	v_cndmask_b32_e64 v39, v55, v57, s[0:1]
	v_pk_mul_f32 v[38:39], v[52:53], v[38:39]
	s_nop 1
	v_cvt_pk_bf16_f32 v37, v38, v39
	v_lshl_add_u64 v[38:39], v[136:137], 1, s[26:27]
	global_store_dwordx2 v[38:39], v[36:37], off
	v_lshlrev_b32_e32 v36, 16, v96
	v_and_b32_e32 v37, 0xffff0000, v96
	v_lshlrev_b32_e32 v38, 16, v97
	v_and_b32_e32 v39, 0xffff0000, v97
	s_nop 1
	v_mov_b32_dpp v50, v36 row_ror:1 row_mask:0xf bank_mask:0xf
	v_mov_b32_dpp v51, v37 row_ror:1 row_mask:0xf bank_mask:0xf
	v_mov_b32_dpp v52, v38 row_ror:1 row_mask:0xf bank_mask:0xf
	v_mov_b32_dpp v53, v39 row_ror:1 row_mask:0xf bank_mask:0xf
	v_mov_b32_dpp v54, v36 row_ror:2 row_mask:0xf bank_mask:0xf
	v_mov_b32_dpp v56, v37 row_ror:2 row_mask:0xf bank_mask:0xf
	v_mov_b32_dpp v55, v38 row_ror:2 row_mask:0xf bank_mask:0xf
	v_mov_b32_dpp v57, v39 row_ror:2 row_mask:0xf bank_mask:0xf
	s_and_saveexec_b64 s[0:1], vcc
	s_cbranch_execz .LBB0_1446
	v_add_u32_e32 v136, v46, v47
	v_lshl_add_u64 v[58:59], v[136:137], 2, s[28:29]
	global_store_dwordx4 v[58:59], v[36:39], off
